# post phase: cross-row steps of the 64-lane sums use v_permlane16_swap / v_permlane32_swap (VALU) instead of ds_bpermute round trips
# baseline (speedup 1.0000x reference)
.LBB0_537:
	s_xor_b64 s[0:1], s[12:13], -1
	s_or_b32 s12, s10, 1
	s_ashr_i32 s13, s12, 31
	s_mul_i32 s11, s12, 0x1e20
	s_mul_hi_i32 s4, s12, 0x1e20
	s_add_u32 s34, s42, s11
	s_addc_u32 s35, s43, s4
	s_lshl_b64 s[90:91], s[12:13], 11
	v_lshl_add_u64 v[60:61], v[40:41], 0, s[90:91]
	v_lshl_add_u64 v[6:7], s[34:35], 0, v[38:39]
	s_lshl_b64 s[12:13], s[12:13], 10
	global_load_ushort v161, v[60:61], off
	global_load_ushort v162, v[60:61], off offset:512
	global_load_ushort v67, v[60:61], off offset:1024
	global_load_ushort v1, v[60:61], off offset:1536
	v_add_co_u32_e32 v8, vcc, s7, v6
	v_lshl_add_u64 v[10:11], v[42:43], 0, s[12:13]
	s_nop 0
	v_addc_co_u32_e32 v9, vcc, 0, v7, vcc
	global_load_ushort v3, v[10:11], off offset:512
	v_lshl_add_u64 v[10:11], v[20:21], 1, s[34:35]
	s_movk_i32 s4, 0xf000
	s_or_b32 s12, s10, 2
	v_add_co_u32_e32 v10, vcc, s4, v10
	s_ashr_i32 s13, s12, 31
	s_nop 0
	v_addc_co_u32_e32 v11, vcc, -1, v11, vcc
	s_lshl_b64 s[34:35], s[12:13], 11
	global_load_ushort v5, v[10:11], off offset:-3616
	global_load_ushort v94, v[6:7], off offset:1536
	global_load_ushort v95, v[6:7], off offset:3072
	global_load_ushort v96, v[8:9], off offset:3072
	global_load_ushort v166, v[6:7], off offset:3584
	global_load_ushort v165, v[8:9], off offset:128
	global_load_ushort v160, v[8:9], off offset:640
	global_load_ushort v97, v[6:7], off offset:-3488
	global_load_ushort v98, v[6:7], off offset:-2976
	v_lshl_add_u64 v[56:57], v[40:41], 0, s[34:35]
	v_mad_i64_i32 v[6:7], s[34:35], s12, v86, v[46:47]
	v_add_co_u32_e32 v8, vcc, s7, v6
	s_lshl_b64 s[12:13], s[12:13], 10
	global_load_ushort v149, v[56:57], off
	global_load_ushort v150, v[56:57], off offset:512
	global_load_ushort v65, v[56:57], off offset:1024
	global_load_ushort v99, v[56:57], off offset:1536
	v_addc_co_u32_e32 v9, vcc, 0, v7, vcc
	global_load_ushort v101, v[6:7], off offset:1536
	global_load_ushort v102, v[6:7], off offset:3072
	global_load_ushort v103, v[8:9], off offset:3072
	global_load_ushort v151, v[6:7], off offset:3584
	global_load_ushort v152, v[8:9], off offset:128
	global_load_ushort v147, v[8:9], off offset:640
	v_lshl_add_u64 v[6:7], v[42:43], 0, s[12:13]
	s_or_b32 s12, s10, 3
	s_ashr_i32 s13, s12, 31
	s_lshl_b64 s[34:35], s[12:13], 11
	global_load_ushort v108, v[6:7], off offset:512
	v_lshl_add_u64 v[52:53], v[40:41], 0, s[34:35]
	v_mad_i64_i32 v[6:7], s[34:35], s12, v86, v[46:47]
	v_add_co_u32_e32 v8, vcc, s7, v6
	s_lshl_b64 s[12:13], s[12:13], 10
	global_load_ushort v136, v[52:53], off
	global_load_ushort v137, v[52:53], off offset:512
	global_load_ushort v59, v[52:53], off offset:1024
	global_load_ushort v110, v[52:53], off offset:1536
	v_addc_co_u32_e32 v9, vcc, 0, v7, vcc
	global_load_ushort v111, v[6:7], off offset:1536
	global_load_ushort v112, v[6:7], off offset:3072
	global_load_ushort v113, v[8:9], off offset:3072
	global_load_ushort v143, v[6:7], off offset:3584
	global_load_ushort v144, v[8:9], off offset:128
	global_load_ushort v135, v[8:9], off offset:640
	v_lshl_add_u64 v[6:7], v[42:43], 0, s[12:13]
	s_or_b32 s12, s10, 4
	s_ashr_i32 s13, s12, 31
	s_lshl_b64 s[34:35], s[12:13], 11
	global_load_ushort v114, v[6:7], off offset:512
	v_lshl_add_u64 v[50:51], v[40:41], 0, s[34:35]
	v_mad_i64_i32 v[6:7], s[34:35], s12, v86, v[46:47]
	v_add_co_u32_e32 v8, vcc, s7, v6
	s_lshl_b64 s[12:13], s[12:13], 10
	global_load_ushort v123, v[50:51], off
	global_load_ushort v124, v[50:51], off offset:512
	global_load_ushort v55, v[50:51], off offset:1024
	global_load_ushort v115, v[50:51], off offset:1536
	v_addc_co_u32_e32 v9, vcc, 0, v7, vcc
	global_load_ushort v116, v[6:7], off offset:1536
	global_load_ushort v119, v[6:7], off offset:3072
	global_load_ushort v125, v[8:9], off offset:3072
	global_load_ushort v131, v[6:7], off offset:3584
	global_load_ushort v132, v[8:9], off offset:128
	global_load_ushort v122, v[8:9], off offset:640
	v_lshl_add_u64 v[6:7], v[42:43], 0, s[12:13]
	s_or_b32 s12, s10, 5
	s_ashr_i32 s13, s12, 31
	s_lshl_b64 s[34:35], s[12:13], 11
	global_load_ushort v129, v[6:7], off offset:512
	v_lshl_add_u64 v[14:15], v[40:41], 0, s[34:35]
	v_mad_i64_i32 v[6:7], s[34:35], s12, v86, v[46:47]
	v_add_co_u32_e32 v8, vcc, s7, v6
	s_lshl_b64 s[12:13], s[12:13], 10
	global_load_ushort v49, v[14:15], off offset:1024
	global_load_ushort v169, v[14:15], off offset:1536
	v_addc_co_u32_e32 v9, vcc, 0, v7, vcc
	global_load_ushort v172, v[6:7], off offset:1536
	global_load_ushort v173, v[6:7], off offset:3072
	global_load_ushort v176, v[8:9], off offset:3072
	global_load_ushort v117, v[6:7], off offset:3584
	global_load_ushort v118, v[8:9], off offset:128
	global_load_ushort v109, v[8:9], off offset:640
	v_lshl_add_u64 v[6:7], v[42:43], 0, s[12:13]
	global_load_ushort v177, v[6:7], off offset:512
	v_cvt_f32_f16_e32 v185, v69
	s_waitcnt vmcnt(60)
	v_cvt_f32_f16_e32 v187, v66
	s_waitcnt vmcnt(57)
	v_cvt_f32_f16_e32 v190, v167
	v_cvt_f32_f16_e32 v192, v58
	v_cvt_f32_f16_e32 v189, v168
	v_cvt_f32_f16_e32 v171, v48
	s_waitcnt vmcnt(52)
	v_cvt_f32_f16_e32 v66, v1
	v_add_f32_dpp v1, v185, v185 row_ror:8 row_mask:0xf bank_mask:0xf bound_ctrl:1
	v_sub_f32_e32 v0, v0, v189
	v_cvt_f32_f16_e32 v170, v54
	v_add_f32_dpp v1, v1, v1 row_ror:4 row_mask:0xf bank_mask:0xf bound_ctrl:1
	v_fma_mix_f32 v0, v75, v0, v168 op_sel_hi:[0,0,1]
	s_waitcnt vmcnt(51)
	v_cvt_f32_f16_e32 v200, v3
	v_add_f32_dpp v1, v1, v1 row_ror:2 row_mask:0xf bank_mask:0xf bound_ctrl:1
	s_or_b32 s12, s10, 6
	s_ashr_i32 s13, s12, 31
	v_add_f32_dpp v1, v1, v1 row_ror:1 row_mask:0xf bank_mask:0xf bound_ctrl:1
	v_mov_b32_e32 v3, v1
	s_nop 1
	v_permlane16_swap_b32_e32 v3, v3
	s_lshl_b64 s[34:35], s[12:13], 11
	v_lshl_add_u64 v[10:11], v[40:41], 0, s[34:35]
	v_mad_i64_i32 v[6:7], s[34:35], s12, v86, v[46:47]
	s_waitcnt lgkmcnt(0)
	v_add_f32_e32 v1, v1, v3
	v_mov_b32_e32 v3, v1
	s_nop 1
	v_permlane32_swap_b32_e32 v3, v3
	v_add_co_u32_e32 v8, vcc, s7, v6
	s_lshl_b64 s[12:13], s[12:13], 10
	s_or_b32 s10, s10, 7
	s_waitcnt lgkmcnt(0)
	v_add_f32_e32 v1, v1, v3
	v_fma_mix_f32 v69, v1, s84, v69 op_sel_hi:[0,0,1]
	v_sub_f32_e32 v1, v2, v190
	v_add_f32_e32 v2, -1.0, v192
	v_fma_mix_f32 v1, v76, v1, v167 op_sel_hi:[0,0,1]
	v_fma_f32 v2, v74, v2, 1.0
	v_mul_f32_e32 v1, v2, v1
	v_mul_f32_e32 v0, v0, v1
	v_mul_f32_e32 v1, v73, v0
	v_mov_b32_e32 v2, 0
	v_mov_b32_e32 v3, 0
	global_load_ushort v13, v[10:11], off offset:1024
	global_load_ushort v178, v[10:11], off offset:1536
	v_mov_b32_dpp v2, v1 row_ror:8 row_mask:0xf bank_mask:0xf
	v_fmac_f32_e32 v2, v73, v0
	v_addc_co_u32_e32 v9, vcc, 0, v7, vcc
	s_waitcnt vmcnt(26)
	v_cvt_f32_f16_e32 v141, v113
	v_add_f32_dpp v0, v2, v2 row_ror:4 row_mask:0xf bank_mask:0xf bound_ctrl:1
	v_mov_b32_e32 v2, 0
	global_load_ushort v179, v[6:7], off offset:1536
	global_load_ushort v180, v[6:7], off offset:3072
	global_load_ushort v181, v[8:9], off offset:3072
	global_load_ushort v104, v[6:7], off offset:3584
	global_load_ushort v105, v[8:9], off offset:128
	global_load_ushort v100, v[8:9], off offset:640
	v_add_f32_dpp v167, v0, v0 row_ror:2 row_mask:0xf bank_mask:0xf bound_ctrl:1
	v_lshl_add_u64 v[6:7], v[42:43], 0, s[12:13]
	s_ashr_i32 s11, s10, 31
	s_mul_i32 s12, s10, 0x1e20
	v_add_f32_dpp v167, v167, v167 row_ror:1 row_mask:0xf bank_mask:0xf bound_ctrl:1
	s_mul_hi_i32 s4, s10, 0x1e20
	s_add_u32 s12, s42, s12
	v_cvt_f32_f16_e32 v186, v64
	v_mov_b32_e32 v168, v167
	s_nop 1
	v_permlane16_swap_b32_e32 v168, v168
	s_waitcnt vmcnt(23)
	v_cvt_f32_f16_e32 v134, v116
	s_waitcnt vmcnt(22)
	v_cvt_f32_f16_e32 v133, v119
	s_addc_u32 s13, s43, s4
	v_lshl_add_u64 v[90:91], s[12:13], 0, v[38:39]
	v_add_co_u32_e32 v92, vcc, s7, v90
	s_waitcnt lgkmcnt(0)
	v_add_f32_e32 v167, v167, v168
	v_addc_co_u32_e32 v93, vcc, 0, v91, vcc
	v_mov_b32_e32 v168, v167
	s_nop 1
	v_permlane32_swap_b32_e32 v168, v168
	s_waitcnt vmcnt(17)
	v_cvt_f32_f16_e32 v142, v129
	v_cvt_f32_f16_e32 v191, v164
	s_lshl_b64 s[34:35], s[10:11], 10
	v_lshl_add_u64 v[8:9], v[42:43], 0, s[34:35]
	s_waitcnt lgkmcnt(0)
	v_add_f32_e32 v167, v167, v168
	s_waitcnt vmcnt(14)
	v_cvt_f32_f16_e32 v119, v172
	s_waitcnt vmcnt(13)
	v_cvt_f32_f16_e32 v116, v173
	s_waitcnt vmcnt(12)
	v_cvt_f32_f16_e32 v113, v176
	v_pk_mul_f32 v[172:173], v[170:171], v[170:171]
	v_mov_b32_e32 v176, 0
	v_cvt_f32_f16_e32 v48, v169
	v_mul_f32_e32 v169, 0xbfb8aa3b, v186
	s_waitcnt vmcnt(8)
	v_cvt_f32_f16_e32 v129, v177
	v_mov_b32_e32 v177, 0
	v_mov_b32_dpp v176, v172 row_ror:8 row_mask:0xf bank_mask:0xf
	v_exp_f32_e32 v169, v169
	v_mov_b32_dpp v177, v173 row_ror:8 row_mask:0xf bank_mask:0xf
	v_pk_fma_f32 v[0:1], v[170:171], v[170:171], v[176:177]
	v_sub_f32_e32 v4, v4, v191
	v_add_f32_e32 v169, 1.0, v169
	v_mov_b32_dpp v3, v1 row_ror:4 row_mask:0xf bank_mask:0xf
	v_mov_b32_dpp v2, v0 row_ror:4 row_mask:0xf bank_mask:0xf
	v_pk_add_f32 v[0:1], v[0:1], v[2:3]
	v_mov_b32_e32 v3, 0
	v_mov_b32_e32 v2, 0
	v_rcp_f32_e32 v169, v169
	v_mov_b32_dpp v3, v1 row_ror:2 row_mask:0xf bank_mask:0xf
	v_mov_b32_dpp v2, v0 row_ror:2 row_mask:0xf bank_mask:0xf
	v_pk_add_f32 v[0:1], v[0:1], v[2:3]
	v_mov_b32_e32 v3, 0
	v_mov_b32_e32 v2, 0
	global_load_ushort v182, v[6:7], off offset:512
	global_load_ushort v183, v[8:9], off offset:512
	v_mov_b32_dpp v3, v1 row_ror:1 row_mask:0xf bank_mask:0xf
	v_mov_b32_dpp v2, v0 row_ror:1 row_mask:0xf bank_mask:0xf
	v_pk_add_f32 v[0:1], v[0:1], v[2:3]
	v_mov_b32_e32 v3, v1
	s_nop 1
	v_permlane16_swap_b32_e32 v3, v3
	v_mov_b32_e32 v2, v0
	s_nop 1
	v_permlane16_swap_b32_e32 v2, v2
	v_lshl_add_u64 v[6:7], v[24:25], 1, s[12:13]
	v_lshl_add_u64 v[8:9], v[22:23], 1, s[12:13]
	s_lshl_b64 s[10:11], s[10:11], 11
	v_fma_mix_f32 v164, v77, v4, v164 op_sel_hi:[0,0,1]
	s_waitcnt lgkmcnt(0)
	v_pk_add_f32 v[0:1], v[0:1], v[2:3]
	v_mov_b32_e32 v3, v1
	s_nop 1
	v_permlane32_swap_b32_e32 v3, v3
	v_mov_b32_e32 v2, v0
	s_nop 1
	v_permlane32_swap_b32_e32 v2, v2
	v_mul_f32_e32 v4, v169, v186
	global_load_ushort v18, v[6:7], off
	global_load_ushort v88, v[8:9], off
	global_load_ushort v89, v[90:91], off offset:3584
	s_nop 0
	global_load_ushort v8, v[92:93], off offset:3072
	global_load_ushort v184, v[90:91], off offset:3072
	s_nop 0
	global_load_ushort v90, v[90:91], off offset:1536
	v_lshl_add_u64 v[6:7], v[40:41], 0, s[10:11]
	v_cvt_f32_f16_e32 v68, v12
	s_waitcnt lgkmcnt(0)
	v_pk_add_f32 v[2:3], v[0:1], v[2:3]
	v_mov_b64_e32 v[0:1], s[8:9]
	v_pk_fma_f32 v[2:3], v[2:3], s[6:7], v[0:1] op_sel_hi:[1,0,0]
	global_load_ushort v91, v[6:7], off offset:1536
	global_load_ushort v120, v[14:15], off
	global_load_ushort v121, v[14:15], off offset:512
	global_load_ushort v106, v[10:11], off
	global_load_ushort v107, v[10:11], off offset:512
	v_mul_f32_e32 v172, 0x4b800000, v3
	v_cmp_gt_f32_e32 vcc, s85, v3
	v_mov_b32_e32 v169, 0
	v_cvt_f32_f16_e32 v193, v67
	v_cndmask_b32_e32 v3, v3, v172, vcc
	v_rsq_f32_e32 v3, v3
	v_cvt_f32_f16_e32 v188, v87
	v_cvt_f32_f16_e32 v198, v165
	v_cvt_f32_f16_e32 v202, v97
	v_mul_f32_e32 v168, 0x45800000, v3
	v_cndmask_b32_e32 v3, v3, v168, vcc
	v_mul_f32_e32 v3, v3, v171
	v_mul_f32_e32 v3, v17, v3
	v_fma_mixlo_f16 v3, v4, v3, 0
	global_store_short v[62:63], v3, off
	v_mul_f32_e32 v3, 0x4b800000, v2
	v_cmp_gt_f32_e32 vcc, s85, v2
	v_mov_b32_e32 v168, 0
	v_cvt_f32_f16_e32 v197, v166
	v_cndmask_b32_e32 v2, v2, v3, vcc
	v_rsq_f32_e32 v4, v2
	v_mul_f32_e32 v2, 0xbfb8aa3b, v187
	v_exp_f32_e32 v171, v2
	v_pk_mul_f32 v[2:3], v[68:69], v[68:69]
	v_mul_f32_e32 v172, 0x45800000, v4
	v_cndmask_b32_e32 v4, v4, v172, vcc
	v_mov_b32_dpp v168, v2 row_ror:8 row_mask:0xf bank_mask:0xf
	v_mov_b32_dpp v169, v3 row_ror:8 row_mask:0xf bank_mask:0xf
	v_pk_fma_f32 v[2:3], v[68:69], v[68:69], v[168:169]
	v_mov_b32_e32 v168, 0
	v_mov_b32_e32 v169, 0
	v_add_f32_e32 v171, 1.0, v171
	v_mov_b32_dpp v168, v2 row_ror:4 row_mask:0xf bank_mask:0xf
	v_mov_b32_dpp v169, v3 row_ror:4 row_mask:0xf bank_mask:0xf
	v_pk_add_f32 v[2:3], v[2:3], v[168:169]
	v_mov_b32_e32 v168, 0
	v_mov_b32_e32 v169, 0
	v_rcp_f32_e32 v171, v171
	v_mov_b32_dpp v168, v2 row_ror:2 row_mask:0xf bank_mask:0xf
	v_mov_b32_dpp v169, v3 row_ror:2 row_mask:0xf bank_mask:0xf
	v_pk_add_f32 v[2:3], v[2:3], v[168:169]
	v_mov_b32_e32 v168, 0
	v_mov_b32_e32 v169, 0
	v_mul_f32_e32 v4, v4, v170
	v_mov_b32_dpp v168, v2 row_ror:1 row_mask:0xf bank_mask:0xf
	v_mov_b32_dpp v169, v3 row_ror:1 row_mask:0xf bank_mask:0xf
	v_pk_add_f32 v[2:3], v[2:3], v[168:169]
	v_mov_b32_e32 v168, v2
	s_nop 1
	v_permlane16_swap_b32_e32 v168, v168
	v_mov_b32_e32 v169, v3
	s_nop 1
	v_permlane16_swap_b32_e32 v169, v169
	v_mul_f32_e32 v4, v70, v4
	v_mul_f32_e32 v170, v171, v187
	v_fma_mixlo_f16 v4, v170, v4, 0
	global_store_short v[62:63], v4, off offset:512
	s_waitcnt lgkmcnt(0)
	v_pk_add_f32 v[2:3], v[2:3], v[168:169]
	v_mov_b32_e32 v168, v2
	s_nop 1
	v_permlane32_swap_b32_e32 v168, v168
	v_mov_b32_e32 v169, v3
	s_nop 1
	v_permlane32_swap_b32_e32 v169, v169
	v_lshl_add_u32 v4, s88, 10, v84
	v_cvt_f32_f16_e32 v201, v5
	v_cvt_f32_f16_e32 v194, v94
	v_cvt_f32_f16_e32 v199, v160
	s_waitcnt lgkmcnt(0)
	v_pk_add_f32 v[168:169], v[2:3], v[168:169]
	v_mov_b64_e32 v[2:3], s[8:9]
	v_pk_fma_f32 v[168:169], v[168:169], s[6:7], v[2:3] op_sel_hi:[1,0,1]
	v_cvt_f32_f16_e32 v203, v98
	v_mul_f32_e32 v170, 0x4b800000, v169
	v_cmp_gt_f32_e32 vcc, s85, v169
	v_cvt_f32_f16_e32 v195, v95
	v_cvt_f32_f16_e32 v204, v65
	v_cndmask_b32_e32 v169, v169, v170, vcc
	v_rsq_f32_e32 v169, v169
	ds_read2st64_b32 v[170:171], v4 offset0:32 offset1:36
	v_cvt_f32_f16_e32 v196, v96
	v_cvt_f32_f16_e32 v154, v152
	v_mul_f32_e32 v172, 0x45800000, v169
	v_cndmask_b32_e32 v169, v169, v172, vcc
	v_mul_f32_e32 v69, v69, v169
	v_fma_f32 v69, v71, v69, v72
	v_fmac_f32_e32 v69, v164, v167
	v_add_f32_dpp v167, v193, v193 row_ror:8 row_mask:0xf bank_mask:0xf bound_ctrl:1
	s_waitcnt lgkmcnt(0)
	v_fma_mixlo_f16 v69, v170, v69, 0
	global_store_short v[62:63], v69, off offset:1024
	v_add_f32_dpp v167, v167, v167 row_ror:4 row_mask:0xf bank_mask:0xf bound_ctrl:1
	v_mul_f32_e32 v69, 0x4b800000, v168
	v_cmp_gt_f32_e32 vcc, s85, v168
	v_add_f32_dpp v167, v167, v167 row_ror:2 row_mask:0xf bank_mask:0xf bound_ctrl:1
	v_mul_f32_e32 v164, 0xbfb8aa3b, v188
	v_cndmask_b32_e32 v69, v168, v69, vcc
	v_add_f32_dpp v167, v167, v167 row_ror:1 row_mask:0xf bank_mask:0xf bound_ctrl:1
	v_exp_f32_e32 v164, v164
	v_mov_b32_e32 v168, v167
	s_nop 1
	v_permlane16_swap_b32_e32 v168, v168
	v_rsq_f32_e32 v69, v69
	v_cvt_f32_f16_e32 v205, v108
	v_add_f32_e32 v164, 1.0, v164
	v_rcp_f32_e32 v164, v164
	s_waitcnt lgkmcnt(0)
	v_add_f32_e32 v167, v167, v168
	v_mov_b32_e32 v168, v167
	s_nop 1
	v_permlane32_swap_b32_e32 v168, v168
	v_mul_f32_e32 v169, 0x45800000, v69
	v_cndmask_b32_e32 v69, v69, v169, vcc
	v_mul_f32_e32 v68, v69, v68
	v_mul_f32_e32 v69, v164, v188
	v_fma_mixlo_f16 v68, v69, v68, 0
	global_store_short v[62:63], v68, off offset:1536
	s_waitcnt lgkmcnt(0)
	v_add_f32_e32 v62, v167, v168
	v_sub_f32_e32 v63, v202, v198
	v_add_f32_e32 v68, -1.0, v200
	v_fma_mix_f32 v67, v62, s84, v67 op_sel_hi:[0,0,1]
	v_sub_f32_e32 v62, v201, v197
	v_fma_mix_f32 v63, v76, v63, v165 op_sel_hi:[0,0,1]
	v_fma_f32 v68, v74, v68, 1.0
	v_fma_mix_f32 v62, v75, v62, v166 op_sel_hi:[0,0,1]
	v_mul_f32_e32 v63, v68, v63
	v_mul_f32_e32 v68, v62, v63
	v_mul_f32_e32 v62, v73, v68
	v_mov_b32_e32 v69, 0
	v_cvt_f32_f16_e32 v63, v161
	v_mov_b32_e32 v165, 0
	v_mov_b32_dpp v69, v62 row_ror:8 row_mask:0xf bank_mask:0xf
	v_cvt_f32_f16_e32 v62, v162
	v_fmac_f32_e32 v69, v73, v68
	v_mov_b32_e32 v164, 0
	v_mul_f32_e32 v167, 0xbfb8aa3b, v194
	v_add_f32_dpp v68, v69, v69 row_ror:4 row_mask:0xf bank_mask:0xf bound_ctrl:1
	v_exp_f32_e32 v167, v167
	v_sub_f32_e32 v166, v203, v199
	v_add_f32_dpp v161, v68, v68 row_ror:2 row_mask:0xf bank_mask:0xf bound_ctrl:1
	v_pk_mul_f32 v[68:69], v[62:63], v[62:63]
	v_add_f32_e32 v167, 1.0, v167
	v_add_f32_dpp v161, v161, v161 row_ror:1 row_mask:0xf bank_mask:0xf bound_ctrl:1
	v_mov_b32_dpp v165, v69 row_ror:8 row_mask:0xf bank_mask:0xf
	v_mov_b32_dpp v164, v68 row_ror:8 row_mask:0xf bank_mask:0xf
	v_pk_fma_f32 v[68:69], v[62:63], v[62:63], v[164:165]
	v_mov_b32_e32 v165, 0
	v_mov_b32_e32 v164, 0
	v_mov_b32_e32 v162, v161
	s_nop 1
	v_permlane16_swap_b32_e32 v162, v162
	v_mov_b32_dpp v165, v69 row_ror:4 row_mask:0xf bank_mask:0xf
	v_mov_b32_dpp v164, v68 row_ror:4 row_mask:0xf bank_mask:0xf
	v_pk_add_f32 v[68:69], v[68:69], v[164:165]
	v_mov_b32_e32 v165, 0
	v_mov_b32_e32 v164, 0
	s_waitcnt lgkmcnt(0)
	v_add_f32_e32 v161, v161, v162
	v_mov_b32_dpp v165, v69 row_ror:2 row_mask:0xf bank_mask:0xf
	v_mov_b32_dpp v164, v68 row_ror:2 row_mask:0xf bank_mask:0xf
	v_pk_add_f32 v[68:69], v[68:69], v[164:165]
	v_mov_b32_e32 v165, 0
	v_mov_b32_e32 v164, 0
	v_mov_b32_e32 v162, v161
	s_nop 1
	v_permlane32_swap_b32_e32 v162, v162
	v_mov_b32_dpp v165, v69 row_ror:1 row_mask:0xf bank_mask:0xf
	v_mov_b32_dpp v164, v68 row_ror:1 row_mask:0xf bank_mask:0xf
	v_pk_add_f32 v[68:69], v[68:69], v[164:165]
	v_mov_b32_e32 v165, v69
	s_nop 1
	v_permlane16_swap_b32_e32 v165, v165
	v_mov_b32_e32 v164, v68
	s_nop 1
	v_permlane16_swap_b32_e32 v164, v164
	v_rcp_f32_e32 v167, v167
	s_waitcnt lgkmcnt(2)
	v_add_f32_e32 v162, v161, v162
	v_cvt_f32_f16_e32 v155, v151
	v_cvt_f32_f16_e32 v163, v101
	s_waitcnt lgkmcnt(0)
	v_pk_add_f32 v[68:69], v[68:69], v[164:165]
	v_mov_b32_e32 v165, v69
	s_nop 1
	v_permlane32_swap_b32_e32 v165, v165
	v_mov_b32_e32 v164, v68
	s_nop 1
	v_permlane32_swap_b32_e32 v164, v164
	v_cvt_f32_f16_e32 v153, v147
	v_cvt_f32_f16_e32 v159, v102
	v_cvt_f32_f16_e32 v64, v99
	v_cvt_f32_f16_e32 v158, v59
	s_waitcnt lgkmcnt(0)
	v_pk_add_f32 v[68:69], v[68:69], v[164:165]
	v_cvt_f32_f16_e32 v156, v103
	v_pk_fma_f32 v[68:69], v[68:69], s[6:7], v[0:1] op_sel_hi:[1,0,0]
	v_cvt_f32_f16_e32 v139, v144
	v_mul_f32_e32 v164, 0x4b800000, v69
	v_cmp_gt_f32_e32 vcc, s85, v69
	v_cvt_f32_f16_e32 v157, v114
	v_cvt_f32_f16_e32 v140, v143
	v_cndmask_b32_e32 v69, v69, v164, vcc
	v_rsq_f32_e32 v69, v69
	v_fma_mix_f32 v164, v77, v166, v160 op_sel_hi:[0,0,1]
	v_mul_f32_e32 v160, v167, v194
	v_cvt_f32_f16_e32 v148, v111
	v_mul_f32_e32 v161, 0x45800000, v69
	v_cndmask_b32_e32 v69, v69, v161, vcc
	v_mul_f32_e32 v63, v69, v63
	v_mul_f32_e32 v63, v17, v63
	v_fma_mixlo_f16 v63, v160, v63, 0
	global_store_short v[60:61], v63, off
	v_mul_f32_e32 v63, 0x4b800000, v68
	v_cmp_gt_f32_e32 vcc, s85, v68
	v_mov_b32_e32 v160, 0
	v_mov_b32_e32 v161, 0
	v_cndmask_b32_e32 v63, v68, v63, vcc
	v_pk_mul_f32 v[68:69], v[66:67], v[66:67]
	v_rsq_f32_e32 v63, v63
	v_cvt_f32_f16_e32 v58, v110
	v_mov_b32_dpp v160, v68 row_ror:8 row_mask:0xf bank_mask:0xf
	v_mov_b32_dpp v161, v69 row_ror:8 row_mask:0xf bank_mask:0xf
	v_pk_fma_f32 v[68:69], v[66:67], v[66:67], v[160:161]
	v_mov_b32_e32 v160, 0
	v_mov_b32_e32 v161, 0
	v_mul_f32_e32 v165, 0x45800000, v63
	v_mov_b32_dpp v160, v68 row_ror:4 row_mask:0xf bank_mask:0xf
	v_mov_b32_dpp v161, v69 row_ror:4 row_mask:0xf bank_mask:0xf
	v_pk_add_f32 v[68:69], v[68:69], v[160:161]
	v_mov_b32_e32 v160, 0
	v_mov_b32_e32 v161, 0
	v_cndmask_b32_e32 v63, v63, v165, vcc
	v_mov_b32_dpp v160, v68 row_ror:2 row_mask:0xf bank_mask:0xf
	v_mov_b32_dpp v161, v69 row_ror:2 row_mask:0xf bank_mask:0xf
	v_pk_add_f32 v[68:69], v[68:69], v[160:161]
	v_mov_b32_e32 v160, 0
	v_mov_b32_e32 v161, 0
	v_mul_f32_e32 v165, 0xbfb8aa3b, v195
	v_mov_b32_dpp v160, v68 row_ror:1 row_mask:0xf bank_mask:0xf
	v_mov_b32_dpp v161, v69 row_ror:1 row_mask:0xf bank_mask:0xf
	v_pk_add_f32 v[68:69], v[68:69], v[160:161]
	v_mov_b32_e32 v160, v68
	s_nop 1
	v_permlane16_swap_b32_e32 v160, v160
	v_mov_b32_e32 v161, v69
	s_nop 1
	v_permlane16_swap_b32_e32 v161, v161
	v_exp_f32_e32 v165, v165
	v_mul_f32_e32 v62, v63, v62
	v_mul_f32_e32 v166, v70, v62
	v_cvt_f32_f16_e32 v146, v112
	s_waitcnt lgkmcnt(0)
	v_pk_add_f32 v[68:69], v[68:69], v[160:161]
	v_mov_b32_e32 v160, v68
	s_nop 1
	v_permlane32_swap_b32_e32 v160, v160
	v_mov_b32_e32 v161, v69
	s_nop 1
	v_permlane32_swap_b32_e32 v161, v161
	v_add_f32_e32 v62, 1.0, v165
	v_rcp_f32_e32 v165, v62
	v_cvt_f32_f16_e32 v138, v135
	v_cvt_f32_f16_e32 v145, v55
	s_waitcnt lgkmcnt(0)
	v_pk_add_f32 v[62:63], v[68:69], v[160:161]
	v_cvt_f32_f16_e32 v126, v132
	v_pk_fma_f32 v[62:63], v[62:63], s[6:7], v[2:3] op_sel_hi:[1,0,1]
	v_cvt_f32_f16_e32 v127, v131
	v_mul_f32_e32 v68, 0x4b800000, v63
	v_cmp_gt_f32_e32 vcc, s85, v63
	v_cvt_f32_f16_e32 v54, v115
	v_cvt_f32_f16_e32 v128, v125
	v_cndmask_b32_e32 v63, v63, v68, vcc
	v_rsq_f32_e32 v63, v63
	v_mul_f32_e32 v68, v165, v195
	v_fma_mixlo_f16 v68, v68, v166, 0
	global_store_short v[60:61], v68, off offset:512
	v_mul_f32_e32 v68, 0x45800000, v63
	v_cndmask_b32_e32 v63, v63, v68, vcc
	v_mul_f32_e32 v63, v67, v63
	v_fma_f32 v63, v71, v63, v72
	v_fmac_f32_e32 v63, v164, v162
	v_add_f32_dpp v67, v204, v204 row_ror:8 row_mask:0xf bank_mask:0xf bound_ctrl:1
	v_fma_mixlo_f16 v63, v171, v63, 0
	global_store_short v[60:61], v63, off offset:1024
	v_add_f32_dpp v67, v67, v67 row_ror:4 row_mask:0xf bank_mask:0xf bound_ctrl:1
	v_mul_f32_e32 v63, 0x4b800000, v62
	v_cmp_gt_f32_e32 vcc, s85, v62
	v_add_f32_dpp v67, v67, v67 row_ror:2 row_mask:0xf bank_mask:0xf bound_ctrl:1
	v_cvt_f32_f16_e32 v125, v122
	v_cndmask_b32_e32 v62, v62, v63, vcc
	v_mul_f32_e32 v63, 0xbfb8aa3b, v196
	v_add_f32_dpp v67, v67, v67 row_ror:1 row_mask:0xf bank_mask:0xf bound_ctrl:1
	v_exp_f32_e32 v63, v63
	v_mov_b32_e32 v68, v67
	s_nop 1
	v_permlane16_swap_b32_e32 v68, v68
	v_rsq_f32_e32 v62, v62
	v_cvt_f32_f16_e32 v130, v49
	v_add_f32_e32 v63, 1.0, v63
	v_rcp_f32_e32 v63, v63
	s_waitcnt lgkmcnt(0)
	v_add_f32_e32 v67, v67, v68
	v_mov_b32_e32 v68, v67
	s_nop 1
	v_permlane32_swap_b32_e32 v68, v68
	v_mul_f32_e32 v69, 0x45800000, v62
	v_cndmask_b32_e32 v62, v62, v69, vcc
	v_mul_f32_e32 v62, v62, v66
	v_mul_f32_e32 v63, v63, v196
	v_fma_mixlo_f16 v62, v63, v62, 0
	global_store_short v[60:61], v62, off offset:1536
	s_waitcnt lgkmcnt(0)
	v_add_f32_e32 v60, v67, v68
	v_sub_f32_e32 v61, v198, v154
	v_add_f32_e32 v62, -1.0, v205
	v_fma_mix_f32 v65, v60, s84, v65 op_sel_hi:[0,0,1]
	v_sub_f32_e32 v60, v197, v155
	v_fma_mix_f32 v61, v76, v61, v152 op_sel_hi:[0,0,1]
	v_fma_f32 v62, v74, v62, 1.0
	v_fma_mix_f32 v60, v75, v60, v151 op_sel_hi:[0,0,1]
	v_mul_f32_e32 v61, v61, v62
	v_mul_f32_e32 v62, v60, v61
	v_mul_f32_e32 v60, v73, v62
	v_mov_b32_e32 v63, 0
	v_cvt_f32_f16_e32 v61, v149
	v_mov_b32_e32 v67, 0
	v_mov_b32_dpp v63, v60 row_ror:8 row_mask:0xf bank_mask:0xf
	v_cvt_f32_f16_e32 v60, v150
	v_fmac_f32_e32 v63, v73, v62
	v_mov_b32_e32 v66, 0
	v_mul_f32_e32 v150, 0xbfb8aa3b, v163
	v_add_f32_dpp v62, v63, v63 row_ror:4 row_mask:0xf bank_mask:0xf bound_ctrl:1
	v_exp_f32_e32 v150, v150
	v_sub_f32_e32 v68, v199, v153
	v_add_f32_dpp v69, v62, v62 row_ror:2 row_mask:0xf bank_mask:0xf bound_ctrl:1
	v_pk_mul_f32 v[62:63], v[60:61], v[60:61]
	v_add_f32_e32 v150, 1.0, v150
	v_add_f32_dpp v69, v69, v69 row_ror:1 row_mask:0xf bank_mask:0xf bound_ctrl:1
	v_mov_b32_dpp v67, v63 row_ror:8 row_mask:0xf bank_mask:0xf
	v_mov_b32_dpp v66, v62 row_ror:8 row_mask:0xf bank_mask:0xf
	v_pk_fma_f32 v[62:63], v[60:61], v[60:61], v[66:67]
	v_mov_b32_e32 v67, 0
	v_mov_b32_e32 v66, 0
	v_mov_b32_e32 v149, v69
	s_nop 1
	v_permlane16_swap_b32_e32 v149, v149
	v_mov_b32_dpp v67, v63 row_ror:4 row_mask:0xf bank_mask:0xf
	v_mov_b32_dpp v66, v62 row_ror:4 row_mask:0xf bank_mask:0xf
	v_pk_add_f32 v[62:63], v[62:63], v[66:67]
	v_mov_b32_e32 v67, 0
	v_mov_b32_e32 v66, 0
	s_waitcnt lgkmcnt(0)
	v_add_f32_e32 v69, v69, v149
	v_mov_b32_dpp v67, v63 row_ror:2 row_mask:0xf bank_mask:0xf
	v_mov_b32_dpp v66, v62 row_ror:2 row_mask:0xf bank_mask:0xf
	v_pk_add_f32 v[62:63], v[62:63], v[66:67]
	v_mov_b32_e32 v67, 0
	v_mov_b32_e32 v66, 0
	v_mov_b32_e32 v149, v69
	s_nop 1
	v_permlane32_swap_b32_e32 v149, v149
	v_mov_b32_dpp v67, v63 row_ror:1 row_mask:0xf bank_mask:0xf
	v_mov_b32_dpp v66, v62 row_ror:1 row_mask:0xf bank_mask:0xf
	v_pk_add_f32 v[62:63], v[62:63], v[66:67]
	v_mov_b32_e32 v67, v63
	s_nop 1
	v_permlane16_swap_b32_e32 v67, v67
	v_mov_b32_e32 v66, v62
	s_nop 1
	v_permlane16_swap_b32_e32 v66, v66
	v_rcp_f32_e32 v150, v150
	v_fma_mix_f32 v68, v77, v68, v147 op_sel_hi:[0,0,1]
	s_waitcnt lgkmcnt(2)
	v_add_f32_e32 v69, v69, v149
	v_cvt_f32_f16_e32 v111, v118
	s_waitcnt lgkmcnt(0)
	v_pk_add_f32 v[62:63], v[62:63], v[66:67]
	v_mov_b32_e32 v67, v63
	s_nop 1
	v_permlane32_swap_b32_e32 v67, v67
	v_mov_b32_e32 v66, v62
	s_nop 1
	v_permlane32_swap_b32_e32 v66, v66
	v_cvt_f32_f16_e32 v112, v117
	v_cvt_f32_f16_e32 v110, v109
	s_waitcnt vmcnt(28)
	v_cvt_f32_f16_e32 v115, v13
	global_load_ushort v9, v[6:7], off offset:1024
	global_load_ushort v96, v[6:7], off
	s_waitcnt lgkmcnt(0)
	v_pk_add_f32 v[62:63], v[62:63], v[66:67]
	s_waitcnt vmcnt(24)
	v_cvt_f32_f16_e32 v94, v105
	v_pk_fma_f32 v[62:63], v[62:63], s[6:7], v[0:1] op_sel_hi:[1,0,0]
	s_waitcnt vmcnt(22)
	v_cvt_f32_f16_e32 v114, v182
	v_mul_f32_e32 v66, 0x4b800000, v63
	v_cmp_gt_f32_e32 vcc, s85, v63
	v_cvt_f32_f16_e32 v95, v104
	s_waitcnt vmcnt(17)
	v_cvt_f32_f16_e32 v5, v8
	v_cndmask_b32_e32 v63, v63, v66, vcc
	v_rsq_f32_e32 v63, v63
	v_mul_f32_e32 v66, v150, v163
	s_waitcnt vmcnt(14)
	v_cvt_f32_f16_e32 v8, v91
	global_load_ushort v91, v[6:7], off offset:512
	v_mul_f32_e32 v67, 0x45800000, v63
	v_cndmask_b32_e32 v63, v63, v67, vcc
	v_mul_f32_e32 v61, v63, v61
	v_mul_f32_e32 v63, 0x4b800000, v62
	v_cmp_gt_f32_e32 vcc, s85, v62
	v_mul_f32_e32 v61, v17, v61
	v_fma_mixlo_f16 v61, v66, v61, 0
	v_cndmask_b32_e32 v62, v62, v63, vcc
	v_rsq_f32_e32 v147, v62
	v_mul_f32_e32 v62, 0xbfb8aa3b, v159
	v_exp_f32_e32 v149, v62
	v_pk_mul_f32 v[62:63], v[64:65], v[64:65]
	v_mov_b32_e32 v66, 0
	v_mov_b32_e32 v67, 0
	global_store_short v[56:57], v61, off
	v_mov_b32_dpp v66, v62 row_ror:8 row_mask:0xf bank_mask:0xf
	v_mov_b32_dpp v67, v63 row_ror:8 row_mask:0xf bank_mask:0xf
	v_pk_fma_f32 v[62:63], v[64:65], v[64:65], v[66:67]
	v_mov_b32_e32 v66, 0
	v_mov_b32_e32 v67, 0
	v_mul_f32_e32 v61, 0x45800000, v147
	v_mov_b32_dpp v66, v62 row_ror:4 row_mask:0xf bank_mask:0xf
	v_mov_b32_dpp v67, v63 row_ror:4 row_mask:0xf bank_mask:0xf
	v_pk_add_f32 v[62:63], v[62:63], v[66:67]
	v_mov_b32_e32 v66, 0
	v_mov_b32_e32 v67, 0
	v_cndmask_b32_e32 v61, v147, v61, vcc
	v_mov_b32_dpp v66, v62 row_ror:2 row_mask:0xf bank_mask:0xf
	v_mov_b32_dpp v67, v63 row_ror:2 row_mask:0xf bank_mask:0xf
	v_pk_add_f32 v[62:63], v[62:63], v[66:67]
	v_mov_b32_e32 v66, 0
	v_mov_b32_e32 v67, 0
	v_mul_f32_e32 v60, v61, v60
	v_mov_b32_dpp v66, v62 row_ror:1 row_mask:0xf bank_mask:0xf
	v_mov_b32_dpp v67, v63 row_ror:1 row_mask:0xf bank_mask:0xf
	v_pk_add_f32 v[62:63], v[62:63], v[66:67]
	v_mov_b32_e32 v66, v62
	s_nop 1
	v_permlane16_swap_b32_e32 v66, v66
	v_mov_b32_e32 v67, v63
	s_nop 1
	v_permlane16_swap_b32_e32 v67, v67
	v_mul_f32_e32 v147, v70, v60
	v_add_f32_e32 v149, 1.0, v149
	v_rcp_f32_e32 v149, v149
	v_cvt_f32_f16_e32 v108, v179
	s_waitcnt lgkmcnt(0)
	v_pk_add_f32 v[62:63], v[62:63], v[66:67]
	v_mov_b32_e32 v66, v62
	s_nop 1
	v_permlane32_swap_b32_e32 v66, v66
	v_mov_b32_e32 v67, v63
	s_nop 1
	v_permlane32_swap_b32_e32 v67, v67
	v_mul_f32_e32 v149, v149, v159
	v_cvt_f32_f16_e32 v103, v180
	v_cvt_f32_f16_e32 v12, v178
	v_cvt_f32_f16_e32 v92, v100
	s_waitcnt lgkmcnt(0)
	v_pk_add_f32 v[60:61], v[62:63], v[66:67]
	v_cvt_f32_f16_e32 v98, v181
	v_pk_fma_f32 v[60:61], v[60:61], s[6:7], v[2:3] op_sel_hi:[1,0,1]
	v_cvt_f32_f16_e32 v93, v183
	v_mul_f32_e32 v62, 0x4b800000, v61
	v_cmp_gt_f32_e32 vcc, s85, v61
	v_cvt_f32_f16_e32 v99, v88
	v_cvt_f32_f16_e32 v101, v89
	v_cndmask_b32_e32 v61, v61, v62, vcc
	v_rsq_f32_e32 v61, v61
	v_fma_mixlo_f16 v62, v149, v147, 0
	global_store_short v[56:57], v62, off offset:512
	ds_read2st64_b32 v[62:63], v4 offset0:40 offset1:44
	v_mul_f32_e32 v66, 0x45800000, v61
	v_cndmask_b32_e32 v61, v61, v66, vcc
	v_mul_f32_e32 v61, v65, v61
	v_fma_f32 v61, v71, v61, v72
	v_fmac_f32_e32 v61, v68, v69
	s_waitcnt lgkmcnt(0)
	v_fma_mixlo_f16 v61, v62, v61, 0
	v_add_f32_dpp v62, v158, v158 row_ror:8 row_mask:0xf bank_mask:0xf bound_ctrl:1
	global_store_short v[56:57], v61, off offset:1024
	v_mul_f32_e32 v61, 0x4b800000, v60
	v_add_f32_dpp v62, v62, v62 row_ror:4 row_mask:0xf bank_mask:0xf bound_ctrl:1
	v_cmp_gt_f32_e32 vcc, s85, v60
	v_mul_f32_e32 v68, 0xbfb8aa3b, v148
	v_add_f32_dpp v62, v62, v62 row_ror:2 row_mask:0xf bank_mask:0xf bound_ctrl:1
	v_cndmask_b32_e32 v60, v60, v61, vcc
	v_mul_f32_e32 v61, 0xbfb8aa3b, v156
	v_add_f32_dpp v62, v62, v62 row_ror:1 row_mask:0xf bank_mask:0xf bound_ctrl:1
	v_exp_f32_e32 v61, v61
	v_mov_b32_e32 v65, v62
	s_nop 1
	v_permlane16_swap_b32_e32 v65, v65
	v_rsq_f32_e32 v60, v60
	v_exp_f32_e32 v68, v68
	v_add_f32_e32 v61, 1.0, v61
	v_rcp_f32_e32 v61, v61
	s_waitcnt lgkmcnt(0)
	v_add_f32_e32 v62, v62, v65
	v_mov_b32_e32 v65, v62
	s_nop 1
	v_permlane32_swap_b32_e32 v65, v65
	v_mul_f32_e32 v66, 0x45800000, v60
	v_cndmask_b32_e32 v60, v60, v66, vcc
	v_mul_f32_e32 v60, v60, v64
	v_mul_f32_e32 v61, v61, v156
	v_fma_mixlo_f16 v60, v61, v60, 0
	global_store_short v[56:57], v60, off offset:1536
	s_waitcnt lgkmcnt(0)
	v_add_f32_e32 v56, v62, v65
	v_sub_f32_e32 v57, v154, v139
	v_add_f32_e32 v60, -1.0, v157
	v_fma_mix_f32 v59, v56, s84, v59 op_sel_hi:[0,0,1]
	v_sub_f32_e32 v56, v155, v140
	v_fma_mix_f32 v57, v76, v57, v144 op_sel_hi:[0,0,1]
	v_fma_f32 v60, v74, v60, 1.0
	v_fma_mix_f32 v56, v75, v56, v143 op_sel_hi:[0,0,1]
	v_mul_f32_e32 v57, v57, v60
	v_mul_f32_e32 v60, v56, v57
	v_mul_f32_e32 v56, v73, v60
	v_mov_b32_e32 v61, 0
	v_cvt_f32_f16_e32 v57, v136
	v_mov_b32_e32 v65, 0
	v_mov_b32_dpp v61, v56 row_ror:8 row_mask:0xf bank_mask:0xf
	v_cvt_f32_f16_e32 v56, v137
	v_fmac_f32_e32 v61, v73, v60
	v_mov_b32_e32 v64, 0
	v_add_f32_e32 v68, 1.0, v68
	v_add_f32_dpp v60, v61, v61 row_ror:4 row_mask:0xf bank_mask:0xf bound_ctrl:1
	v_rcp_f32_e32 v68, v68
	v_sub_f32_e32 v62, v153, v138
	v_add_f32_dpp v66, v60, v60 row_ror:2 row_mask:0xf bank_mask:0xf bound_ctrl:1
	v_pk_mul_f32 v[60:61], v[56:57], v[56:57]
	v_fma_mix_f32 v62, v77, v62, v135 op_sel_hi:[0,0,1]
	v_add_f32_dpp v66, v66, v66 row_ror:1 row_mask:0xf bank_mask:0xf bound_ctrl:1
	v_mov_b32_dpp v65, v61 row_ror:8 row_mask:0xf bank_mask:0xf
	v_mov_b32_dpp v64, v60 row_ror:8 row_mask:0xf bank_mask:0xf
	v_pk_fma_f32 v[60:61], v[56:57], v[56:57], v[64:65]
	v_mov_b32_e32 v65, 0
	v_mov_b32_e32 v64, 0
	v_mov_b32_e32 v67, v66
	s_nop 1
	v_permlane16_swap_b32_e32 v67, v67
	v_mov_b32_dpp v65, v61 row_ror:4 row_mask:0xf bank_mask:0xf
	v_mov_b32_dpp v64, v60 row_ror:4 row_mask:0xf bank_mask:0xf
	v_pk_add_f32 v[60:61], v[60:61], v[64:65]
	v_mov_b32_e32 v65, 0
	v_mov_b32_e32 v64, 0
	s_waitcnt lgkmcnt(0)
	v_add_f32_e32 v66, v66, v67
	v_mov_b32_dpp v65, v61 row_ror:2 row_mask:0xf bank_mask:0xf
	v_mov_b32_dpp v64, v60 row_ror:2 row_mask:0xf bank_mask:0xf
	v_pk_add_f32 v[60:61], v[60:61], v[64:65]
	v_mov_b32_e32 v65, 0
	v_mov_b32_e32 v64, 0
	v_mov_b32_e32 v67, v66
	s_nop 1
	v_permlane32_swap_b32_e32 v67, v67
	v_mov_b32_dpp v65, v61 row_ror:1 row_mask:0xf bank_mask:0xf
	v_mov_b32_dpp v64, v60 row_ror:1 row_mask:0xf bank_mask:0xf
	v_pk_add_f32 v[60:61], v[60:61], v[64:65]
	v_mov_b32_e32 v65, v61
	s_nop 1
	v_permlane16_swap_b32_e32 v65, v65
	v_mov_b32_e32 v64, v60
	s_nop 1
	v_permlane16_swap_b32_e32 v64, v64
	s_waitcnt lgkmcnt(2)
	v_add_f32_e32 v66, v66, v67
	s_waitcnt vmcnt(6)
	v_cvt_f32_f16_e32 v102, v9
	v_cvt_f32_f16_e32 v90, v90
	v_cvt_f32_f16_e32 v87, v184
	s_waitcnt lgkmcnt(0)
	v_pk_add_f32 v[60:61], v[60:61], v[64:65]
	v_mov_b32_e32 v65, v61
	s_nop 1
	v_permlane32_swap_b32_e32 v65, v65
	v_mov_b32_e32 v64, v60
	s_nop 1
	v_permlane32_swap_b32_e32 v64, v64
	v_cvt_f32_f16_e32 v97, v18
	s_mov_b32 s88, 8
	s_mov_b64 s[12:13], 0
	s_waitcnt lgkmcnt(0)
	v_pk_add_f32 v[60:61], v[60:61], v[64:65]
	s_nop 0
	v_pk_fma_f32 v[60:61], v[60:61], s[6:7], v[0:1] op_sel_hi:[1,0,0]
	s_nop 0
	v_mul_f32_e32 v64, 0x4b800000, v61
	v_cmp_gt_f32_e32 vcc, s85, v61
	s_nop 1
	v_cndmask_b32_e32 v61, v61, v64, vcc
	v_rsq_f32_e32 v61, v61
	v_mul_f32_e32 v64, v68, v148
	v_mul_f32_e32 v65, 0x45800000, v61
	v_cndmask_b32_e32 v61, v61, v65, vcc
	v_mul_f32_e32 v57, v61, v57
	v_mul_f32_e32 v57, v17, v57
	v_fma_mixlo_f16 v57, v64, v57, 0
	global_store_short v[52:53], v57, off
	v_mul_f32_e32 v57, 0x4b800000, v60
	v_cmp_gt_f32_e32 vcc, s85, v60
	v_mov_b32_e32 v64, 0
	v_mov_b32_e32 v65, 0
	v_cndmask_b32_e32 v57, v60, v57, vcc
	v_pk_mul_f32 v[60:61], v[58:59], v[58:59]
	v_rsq_f32_e32 v57, v57
	s_nop 0
	v_mov_b32_dpp v64, v60 row_ror:8 row_mask:0xf bank_mask:0xf
	v_mov_b32_dpp v65, v61 row_ror:8 row_mask:0xf bank_mask:0xf
	v_pk_fma_f32 v[60:61], v[58:59], v[58:59], v[64:65]
	v_mov_b32_e32 v64, 0
	v_mov_b32_e32 v65, 0
	v_mul_f32_e32 v67, 0x45800000, v57
	v_mov_b32_dpp v64, v60 row_ror:4 row_mask:0xf bank_mask:0xf
	v_mov_b32_dpp v65, v61 row_ror:4 row_mask:0xf bank_mask:0xf
	v_pk_add_f32 v[60:61], v[60:61], v[64:65]
	v_mov_b32_e32 v64, 0
	v_mov_b32_e32 v65, 0
	v_cndmask_b32_e32 v57, v57, v67, vcc
	v_mov_b32_dpp v64, v60 row_ror:2 row_mask:0xf bank_mask:0xf
	v_mov_b32_dpp v65, v61 row_ror:2 row_mask:0xf bank_mask:0xf
	v_pk_add_f32 v[60:61], v[60:61], v[64:65]
	v_mov_b32_e32 v64, 0
	v_mov_b32_e32 v65, 0
	v_mul_f32_e32 v67, 0xbfb8aa3b, v146
	v_mov_b32_dpp v64, v60 row_ror:1 row_mask:0xf bank_mask:0xf
	v_mov_b32_dpp v65, v61 row_ror:1 row_mask:0xf bank_mask:0xf
	v_pk_add_f32 v[60:61], v[60:61], v[64:65]
	v_mov_b32_e32 v64, v60
	s_nop 1
	v_permlane16_swap_b32_e32 v64, v64
	v_mov_b32_e32 v65, v61
	s_nop 1
	v_permlane16_swap_b32_e32 v65, v65
	v_exp_f32_e32 v67, v67
	v_mul_f32_e32 v56, v57, v56
	v_mul_f32_e32 v68, v70, v56
	s_waitcnt lgkmcnt(0)
	v_pk_add_f32 v[60:61], v[60:61], v[64:65]
	v_mov_b32_e32 v64, v60
	s_nop 1
	v_permlane32_swap_b32_e32 v64, v64
	v_mov_b32_e32 v65, v61
	s_nop 1
	v_permlane32_swap_b32_e32 v65, v65
	v_add_f32_e32 v56, 1.0, v67
	v_rcp_f32_e32 v67, v56
	s_waitcnt lgkmcnt(0)
	v_pk_add_f32 v[56:57], v[60:61], v[64:65]
	s_nop 0
	v_pk_fma_f32 v[56:57], v[56:57], s[6:7], v[2:3] op_sel_hi:[1,0,1]
	s_nop 0
	v_mul_f32_e32 v60, 0x4b800000, v57
	v_cmp_gt_f32_e32 vcc, s85, v57
	s_nop 1
	v_cndmask_b32_e32 v57, v57, v60, vcc
	v_rsq_f32_e32 v57, v57
	v_mul_f32_e32 v60, v67, v146
	v_fma_mixlo_f16 v60, v60, v68, 0
	global_store_short v[52:53], v60, off offset:512
	v_mul_f32_e32 v60, 0x45800000, v57
	v_cndmask_b32_e32 v57, v57, v60, vcc
	v_mul_f32_e32 v57, v59, v57
	v_fma_f32 v57, v71, v57, v72
	v_fmac_f32_e32 v57, v62, v66
	v_add_f32_dpp v59, v145, v145 row_ror:8 row_mask:0xf bank_mask:0xf bound_ctrl:1
	v_fma_mixlo_f16 v57, v63, v57, 0
	global_store_short v[52:53], v57, off offset:1024
	v_add_f32_dpp v59, v59, v59 row_ror:4 row_mask:0xf bank_mask:0xf bound_ctrl:1
	v_mul_f32_e32 v57, 0x4b800000, v56
	v_cmp_gt_f32_e32 vcc, s85, v56
	v_add_f32_dpp v59, v59, v59 row_ror:2 row_mask:0xf bank_mask:0xf bound_ctrl:1
	v_mul_f32_e32 v63, 0xbfb8aa3b, v134
	v_cndmask_b32_e32 v56, v56, v57, vcc
	v_mul_f32_e32 v57, 0xbfb8aa3b, v141
	v_add_f32_dpp v59, v59, v59 row_ror:1 row_mask:0xf bank_mask:0xf bound_ctrl:1
	v_exp_f32_e32 v57, v57
	v_mov_b32_e32 v60, v59
	s_nop 1
	v_permlane16_swap_b32_e32 v60, v60
	v_rsq_f32_e32 v56, v56
	v_exp_f32_e32 v63, v63
	v_add_f32_e32 v57, 1.0, v57
	v_rcp_f32_e32 v57, v57
	s_waitcnt lgkmcnt(0)
	v_add_f32_e32 v59, v59, v60
	v_mov_b32_e32 v60, v59
	s_nop 1
	v_permlane32_swap_b32_e32 v60, v60
	v_mul_f32_e32 v61, 0x45800000, v56
	v_cndmask_b32_e32 v56, v56, v61, vcc
	v_mul_f32_e32 v56, v56, v58
	v_mul_f32_e32 v57, v57, v141
	v_fma_mixlo_f16 v56, v57, v56, 0
	global_store_short v[52:53], v56, off offset:1536
	s_waitcnt lgkmcnt(0)
	v_add_f32_e32 v52, v59, v60
	v_sub_f32_e32 v53, v139, v126
	v_add_f32_e32 v56, -1.0, v142
	v_fma_mix_f32 v55, v52, s84, v55 op_sel_hi:[0,0,1]
	v_sub_f32_e32 v52, v140, v127
	v_fma_mix_f32 v53, v76, v53, v132 op_sel_hi:[0,0,1]
	v_fma_f32 v56, v74, v56, 1.0
	v_fma_mix_f32 v52, v75, v52, v131 op_sel_hi:[0,0,1]
	v_mul_f32_e32 v53, v53, v56
	v_mul_f32_e32 v56, v52, v53
	v_mul_f32_e32 v52, v73, v56
	v_mov_b32_e32 v57, 0
	v_cvt_f32_f16_e32 v53, v123
	v_mov_b32_e32 v59, 0
	v_mov_b32_dpp v57, v52 row_ror:8 row_mask:0xf bank_mask:0xf
	v_cvt_f32_f16_e32 v52, v124
	v_fmac_f32_e32 v57, v73, v56
	v_mov_b32_e32 v58, 0
	v_add_f32_e32 v63, 1.0, v63
	v_add_f32_dpp v56, v57, v57 row_ror:4 row_mask:0xf bank_mask:0xf bound_ctrl:1
	v_rcp_f32_e32 v63, v63
	v_sub_f32_e32 v60, v138, v125
	v_add_f32_dpp v61, v56, v56 row_ror:2 row_mask:0xf bank_mask:0xf bound_ctrl:1
	v_pk_mul_f32 v[56:57], v[52:53], v[52:53]
	v_fma_mix_f32 v60, v77, v60, v122 op_sel_hi:[0,0,1]
	v_add_f32_dpp v61, v61, v61 row_ror:1 row_mask:0xf bank_mask:0xf bound_ctrl:1
	v_mov_b32_dpp v59, v57 row_ror:8 row_mask:0xf bank_mask:0xf
	v_mov_b32_dpp v58, v56 row_ror:8 row_mask:0xf bank_mask:0xf
	v_pk_fma_f32 v[56:57], v[52:53], v[52:53], v[58:59]
	v_mov_b32_e32 v59, 0
	v_mov_b32_e32 v58, 0
	v_mov_b32_e32 v62, v61
	s_nop 1
	v_permlane16_swap_b32_e32 v62, v62
	v_mov_b32_dpp v59, v57 row_ror:4 row_mask:0xf bank_mask:0xf
	v_mov_b32_dpp v58, v56 row_ror:4 row_mask:0xf bank_mask:0xf
	v_pk_add_f32 v[56:57], v[56:57], v[58:59]
	v_mov_b32_e32 v59, 0
	v_mov_b32_e32 v58, 0
	s_waitcnt lgkmcnt(0)
	v_add_f32_e32 v61, v61, v62
	v_mov_b32_dpp v59, v57 row_ror:2 row_mask:0xf bank_mask:0xf
	v_mov_b32_dpp v58, v56 row_ror:2 row_mask:0xf bank_mask:0xf
	v_pk_add_f32 v[56:57], v[56:57], v[58:59]
	v_mov_b32_e32 v59, 0
	v_mov_b32_e32 v58, 0
	v_mov_b32_e32 v62, v61
	s_nop 1
	v_permlane32_swap_b32_e32 v62, v62
	v_mov_b32_dpp v59, v57 row_ror:1 row_mask:0xf bank_mask:0xf
	v_mov_b32_dpp v58, v56 row_ror:1 row_mask:0xf bank_mask:0xf
	v_pk_add_f32 v[56:57], v[56:57], v[58:59]
	v_mov_b32_e32 v59, v57
	s_nop 1
	v_permlane16_swap_b32_e32 v59, v59
	v_mov_b32_e32 v58, v56
	s_nop 1
	v_permlane16_swap_b32_e32 v58, v58
	s_waitcnt lgkmcnt(2)
	v_add_f32_e32 v61, v61, v62
	s_waitcnt lgkmcnt(0)
	v_pk_add_f32 v[56:57], v[56:57], v[58:59]
	v_mov_b32_e32 v59, v57
	s_nop 1
	v_permlane32_swap_b32_e32 v59, v59
	v_mov_b32_e32 v58, v56
	s_nop 1
	v_permlane32_swap_b32_e32 v58, v58
	s_waitcnt lgkmcnt(0)
	v_pk_add_f32 v[56:57], v[56:57], v[58:59]
	s_nop 0
	v_pk_fma_f32 v[56:57], v[56:57], s[6:7], v[0:1] op_sel_hi:[1,0,0]
	s_nop 0
	v_mul_f32_e32 v58, 0x4b800000, v57
	v_cmp_gt_f32_e32 vcc, s85, v57
	s_nop 1
	v_cndmask_b32_e32 v57, v57, v58, vcc
	v_rsq_f32_e32 v57, v57
	v_mul_f32_e32 v58, v63, v134
	v_mul_f32_e32 v59, 0x45800000, v57
	v_cndmask_b32_e32 v57, v57, v59, vcc
	v_mul_f32_e32 v53, v57, v53
	v_mul_f32_e32 v57, 0x4b800000, v56
	v_cmp_gt_f32_e32 vcc, s85, v56
	v_mul_f32_e32 v53, v17, v53
	v_fma_mixlo_f16 v53, v58, v53, 0
	v_cndmask_b32_e32 v56, v56, v57, vcc
	v_rsq_f32_e32 v62, v56
	v_mul_f32_e32 v56, 0xbfb8aa3b, v133
	v_exp_f32_e32 v63, v56
	v_pk_mul_f32 v[56:57], v[54:55], v[54:55]
	v_mov_b32_e32 v58, 0
	v_mov_b32_e32 v59, 0
	global_store_short v[50:51], v53, off
	v_mov_b32_dpp v58, v56 row_ror:8 row_mask:0xf bank_mask:0xf
	v_mov_b32_dpp v59, v57 row_ror:8 row_mask:0xf bank_mask:0xf
	v_pk_fma_f32 v[56:57], v[54:55], v[54:55], v[58:59]
	v_mov_b32_e32 v58, 0
	v_mov_b32_e32 v59, 0
	v_mul_f32_e32 v53, 0x45800000, v62
	v_mov_b32_dpp v58, v56 row_ror:4 row_mask:0xf bank_mask:0xf
	v_mov_b32_dpp v59, v57 row_ror:4 row_mask:0xf bank_mask:0xf
	v_pk_add_f32 v[56:57], v[56:57], v[58:59]
	v_mov_b32_e32 v58, 0
	v_mov_b32_e32 v59, 0
	v_cndmask_b32_e32 v53, v62, v53, vcc
	v_mov_b32_dpp v58, v56 row_ror:2 row_mask:0xf bank_mask:0xf
	v_mov_b32_dpp v59, v57 row_ror:2 row_mask:0xf bank_mask:0xf
	v_pk_add_f32 v[56:57], v[56:57], v[58:59]
	v_mov_b32_e32 v58, 0
	v_mov_b32_e32 v59, 0
	v_mul_f32_e32 v52, v53, v52
	v_mov_b32_dpp v58, v56 row_ror:1 row_mask:0xf bank_mask:0xf
	v_mov_b32_dpp v59, v57 row_ror:1 row_mask:0xf bank_mask:0xf
	v_pk_add_f32 v[56:57], v[56:57], v[58:59]
	v_mov_b32_e32 v58, v56
	s_nop 1
	v_permlane16_swap_b32_e32 v58, v58
	v_mov_b32_e32 v59, v57
	s_nop 1
	v_permlane16_swap_b32_e32 v59, v59
	v_mul_f32_e32 v62, v70, v52
	v_add_f32_e32 v63, 1.0, v63
	v_rcp_f32_e32 v63, v63
	s_waitcnt lgkmcnt(0)
	v_pk_add_f32 v[56:57], v[56:57], v[58:59]
	v_mov_b32_e32 v58, v56
	s_nop 1
	v_permlane32_swap_b32_e32 v58, v58
	v_mov_b32_e32 v59, v57
	s_nop 1
	v_permlane32_swap_b32_e32 v59, v59
	v_mul_f32_e32 v63, v63, v133
	s_waitcnt lgkmcnt(0)
	v_pk_add_f32 v[52:53], v[56:57], v[58:59]
	s_nop 0
	v_pk_fma_f32 v[52:53], v[52:53], s[6:7], v[2:3] op_sel_hi:[1,0,1]
	s_nop 0
	v_mul_f32_e32 v56, 0x4b800000, v53
	v_cmp_gt_f32_e32 vcc, s85, v53
	s_nop 1
	v_cndmask_b32_e32 v53, v53, v56, vcc
	v_rsq_f32_e32 v53, v53
	v_fma_mixlo_f16 v56, v63, v62, 0
	global_store_short v[50:51], v56, off offset:512
	ds_read2st64_b32 v[56:57], v4 offset0:48 offset1:52
	v_mul_f32_e32 v58, 0x45800000, v53
	v_cndmask_b32_e32 v53, v53, v58, vcc
	v_mul_f32_e32 v53, v55, v53
	v_fma_f32 v53, v71, v53, v72
	v_fmac_f32_e32 v53, v60, v61
	v_add_f32_dpp v55, v130, v130 row_ror:8 row_mask:0xf bank_mask:0xf bound_ctrl:1
	s_waitcnt lgkmcnt(0)
	v_fma_mixlo_f16 v53, v56, v53, 0
	global_store_short v[50:51], v53, off offset:1024
	v_add_f32_dpp v55, v55, v55 row_ror:4 row_mask:0xf bank_mask:0xf bound_ctrl:1
	v_mul_f32_e32 v53, 0x4b800000, v52
	v_cmp_gt_f32_e32 vcc, s85, v52
	v_add_f32_dpp v55, v55, v55 row_ror:2 row_mask:0xf bank_mask:0xf bound_ctrl:1
	v_mul_f32_e32 v60, 0xbfb8aa3b, v119
	v_cndmask_b32_e32 v52, v52, v53, vcc
	v_mul_f32_e32 v53, 0xbfb8aa3b, v128
	v_add_f32_dpp v55, v55, v55 row_ror:1 row_mask:0xf bank_mask:0xf bound_ctrl:1
	v_exp_f32_e32 v53, v53
	v_mov_b32_e32 v56, v55
	s_nop 1
	v_permlane16_swap_b32_e32 v56, v56
	v_rsq_f32_e32 v52, v52
	v_exp_f32_e32 v60, v60
	v_add_f32_e32 v53, 1.0, v53
	v_rcp_f32_e32 v53, v53
	s_waitcnt lgkmcnt(0)
	v_add_f32_e32 v55, v55, v56
	v_mov_b32_e32 v56, v55
	s_nop 1
	v_permlane32_swap_b32_e32 v56, v56
	v_mul_f32_e32 v58, 0x45800000, v52
	v_cndmask_b32_e32 v52, v52, v58, vcc
	v_mul_f32_e32 v52, v52, v54
	v_mul_f32_e32 v53, v53, v128
	v_fma_mixlo_f16 v52, v53, v52, 0
	global_store_short v[50:51], v52, off offset:1536
	s_waitcnt lgkmcnt(0)
	v_add_f32_e32 v50, v55, v56
	v_sub_f32_e32 v51, v126, v111
	v_add_f32_e32 v52, -1.0, v129
	v_fma_mix_f32 v49, v50, s84, v49 op_sel_hi:[0,0,1]
	v_sub_f32_e32 v50, v127, v112
	v_fma_mix_f32 v51, v76, v51, v118 op_sel_hi:[0,0,1]
	v_fma_f32 v52, v74, v52, 1.0
	v_fma_mix_f32 v50, v75, v50, v117 op_sel_hi:[0,0,1]
	v_mul_f32_e32 v51, v51, v52
	v_mul_f32_e32 v52, v50, v51
	v_mul_f32_e32 v50, v73, v52
	v_mov_b32_e32 v53, 0
	v_cvt_f32_f16_e32 v51, v120
	v_mov_b32_e32 v55, 0
	v_mov_b32_dpp v53, v50 row_ror:8 row_mask:0xf bank_mask:0xf
	v_cvt_f32_f16_e32 v50, v121
	v_fmac_f32_e32 v53, v73, v52
	v_mov_b32_e32 v54, 0
	v_add_f32_e32 v60, 1.0, v60
	v_add_f32_dpp v52, v53, v53 row_ror:4 row_mask:0xf bank_mask:0xf bound_ctrl:1
	v_rcp_f32_e32 v60, v60
	v_sub_f32_e32 v56, v125, v110
	v_add_f32_dpp v58, v52, v52 row_ror:2 row_mask:0xf bank_mask:0xf bound_ctrl:1
	v_pk_mul_f32 v[52:53], v[50:51], v[50:51]
	v_fma_mix_f32 v56, v77, v56, v109 op_sel_hi:[0,0,1]
	v_add_f32_dpp v58, v58, v58 row_ror:1 row_mask:0xf bank_mask:0xf bound_ctrl:1
	v_mov_b32_dpp v55, v53 row_ror:8 row_mask:0xf bank_mask:0xf
	v_mov_b32_dpp v54, v52 row_ror:8 row_mask:0xf bank_mask:0xf
	v_pk_fma_f32 v[52:53], v[50:51], v[50:51], v[54:55]
	v_mov_b32_e32 v55, 0
	v_mov_b32_e32 v54, 0
	v_mov_b32_e32 v59, v58
	s_nop 1
	v_permlane16_swap_b32_e32 v59, v59
	v_mov_b32_dpp v55, v53 row_ror:4 row_mask:0xf bank_mask:0xf
	v_mov_b32_dpp v54, v52 row_ror:4 row_mask:0xf bank_mask:0xf
	v_pk_add_f32 v[52:53], v[52:53], v[54:55]
	v_mov_b32_e32 v55, 0
	v_mov_b32_e32 v54, 0
	s_waitcnt lgkmcnt(0)
	v_add_f32_e32 v58, v58, v59
	v_mov_b32_dpp v55, v53 row_ror:2 row_mask:0xf bank_mask:0xf
	v_mov_b32_dpp v54, v52 row_ror:2 row_mask:0xf bank_mask:0xf
	v_pk_add_f32 v[52:53], v[52:53], v[54:55]
	v_mov_b32_e32 v55, 0
	v_mov_b32_e32 v54, 0
	v_mov_b32_e32 v59, v58
	s_nop 1
	v_permlane32_swap_b32_e32 v59, v59
	v_mov_b32_dpp v55, v53 row_ror:1 row_mask:0xf bank_mask:0xf
	v_mov_b32_dpp v54, v52 row_ror:1 row_mask:0xf bank_mask:0xf
	v_pk_add_f32 v[52:53], v[52:53], v[54:55]
	v_mov_b32_e32 v55, v53
	s_nop 1
	v_permlane16_swap_b32_e32 v55, v55
	v_mov_b32_e32 v54, v52
	s_nop 1
	v_permlane16_swap_b32_e32 v54, v54
	s_waitcnt lgkmcnt(2)
	v_add_f32_e32 v58, v58, v59
	s_waitcnt lgkmcnt(0)
	v_pk_add_f32 v[52:53], v[52:53], v[54:55]
	v_mov_b32_e32 v55, v53
	s_nop 1
	v_permlane32_swap_b32_e32 v55, v55
	v_mov_b32_e32 v54, v52
	s_nop 1
	v_permlane32_swap_b32_e32 v54, v54
	s_waitcnt lgkmcnt(0)
	v_pk_add_f32 v[52:53], v[52:53], v[54:55]
	s_nop 0
	v_pk_fma_f32 v[52:53], v[52:53], s[6:7], v[0:1] op_sel_hi:[1,0,0]
	s_nop 0
	v_mul_f32_e32 v54, 0x4b800000, v53
	v_cmp_gt_f32_e32 vcc, s85, v53
	s_nop 1
	v_cndmask_b32_e32 v53, v53, v54, vcc
	v_rsq_f32_e32 v53, v53
	v_mul_f32_e32 v54, v60, v119
	v_mul_f32_e32 v55, 0x45800000, v53
	v_cndmask_b32_e32 v53, v53, v55, vcc
	v_mul_f32_e32 v51, v53, v51
	v_mul_f32_e32 v51, v17, v51
	v_fma_mixlo_f16 v51, v54, v51, 0
	global_store_short v[14:15], v51, off
	v_mul_f32_e32 v51, 0x4b800000, v52
	v_cmp_gt_f32_e32 vcc, s85, v52
	v_mov_b32_e32 v54, 0
	v_mov_b32_e32 v55, 0
	v_cndmask_b32_e32 v51, v52, v51, vcc
	v_pk_mul_f32 v[52:53], v[48:49], v[48:49]
	v_rsq_f32_e32 v51, v51
	s_nop 0
	v_mov_b32_dpp v54, v52 row_ror:8 row_mask:0xf bank_mask:0xf
	v_mov_b32_dpp v55, v53 row_ror:8 row_mask:0xf bank_mask:0xf
	v_pk_fma_f32 v[52:53], v[48:49], v[48:49], v[54:55]
	v_mov_b32_e32 v54, 0
	v_mov_b32_e32 v55, 0
	v_mul_f32_e32 v59, 0x45800000, v51
	v_mov_b32_dpp v54, v52 row_ror:4 row_mask:0xf bank_mask:0xf
	v_mov_b32_dpp v55, v53 row_ror:4 row_mask:0xf bank_mask:0xf
	v_pk_add_f32 v[52:53], v[52:53], v[54:55]
	v_mov_b32_e32 v54, 0
	v_mov_b32_e32 v55, 0
	v_cndmask_b32_e32 v51, v51, v59, vcc
	v_mov_b32_dpp v54, v52 row_ror:2 row_mask:0xf bank_mask:0xf
	v_mov_b32_dpp v55, v53 row_ror:2 row_mask:0xf bank_mask:0xf
	v_pk_add_f32 v[52:53], v[52:53], v[54:55]
	v_mov_b32_e32 v54, 0
	v_mov_b32_e32 v55, 0
	v_mul_f32_e32 v59, 0xbfb8aa3b, v116
	v_mov_b32_dpp v54, v52 row_ror:1 row_mask:0xf bank_mask:0xf
	v_mov_b32_dpp v55, v53 row_ror:1 row_mask:0xf bank_mask:0xf
	v_pk_add_f32 v[52:53], v[52:53], v[54:55]
	v_mov_b32_e32 v54, v52
	s_nop 1
	v_permlane16_swap_b32_e32 v54, v54
	v_mov_b32_e32 v55, v53
	s_nop 1
	v_permlane16_swap_b32_e32 v55, v55
	v_exp_f32_e32 v59, v59
	v_mul_f32_e32 v50, v51, v50
	v_mul_f32_e32 v60, v70, v50
	s_waitcnt lgkmcnt(0)
	v_pk_add_f32 v[52:53], v[52:53], v[54:55]
	v_mov_b32_e32 v54, v52
	s_nop 1
	v_permlane32_swap_b32_e32 v54, v54
	v_mov_b32_e32 v55, v53
	s_nop 1
	v_permlane32_swap_b32_e32 v55, v55
	v_add_f32_e32 v50, 1.0, v59
	v_rcp_f32_e32 v59, v50
	s_waitcnt lgkmcnt(0)
	v_pk_add_f32 v[50:51], v[52:53], v[54:55]
	s_nop 0
	v_pk_fma_f32 v[50:51], v[50:51], s[6:7], v[2:3] op_sel_hi:[1,0,1]
	v_mul_f32_e32 v55, 0xbfb8aa3b, v108
	v_mul_f32_e32 v52, 0x4b800000, v51
	v_cmp_gt_f32_e32 vcc, s85, v51
	v_exp_f32_e32 v55, v55
	s_nop 0
	v_cndmask_b32_e32 v51, v51, v52, vcc
	v_rsq_f32_e32 v51, v51
	v_mul_f32_e32 v52, v59, v116
	v_fma_mixlo_f16 v52, v52, v60, 0
	global_store_short v[14:15], v52, off offset:512
	v_mul_f32_e32 v52, 0x45800000, v51
	v_cndmask_b32_e32 v51, v51, v52, vcc
	v_mul_f32_e32 v49, v49, v51
	v_fma_f32 v49, v71, v49, v72
	v_fmac_f32_e32 v49, v56, v58
	v_add_f32_dpp v51, v115, v115 row_ror:8 row_mask:0xf bank_mask:0xf bound_ctrl:1
	v_fma_mixlo_f16 v49, v57, v49, 0
	global_store_short v[14:15], v49, off offset:1024
	v_add_f32_dpp v51, v51, v51 row_ror:4 row_mask:0xf bank_mask:0xf bound_ctrl:1
	v_mul_f32_e32 v49, 0x4b800000, v50
	v_cmp_gt_f32_e32 vcc, s85, v50
	v_add_f32_dpp v51, v51, v51 row_ror:2 row_mask:0xf bank_mask:0xf bound_ctrl:1
	v_add_f32_e32 v55, 1.0, v55
	v_cndmask_b32_e32 v49, v50, v49, vcc
	v_mul_f32_e32 v50, 0xbfb8aa3b, v113
	v_add_f32_dpp v51, v51, v51 row_ror:1 row_mask:0xf bank_mask:0xf bound_ctrl:1
	v_exp_f32_e32 v50, v50
	v_mov_b32_e32 v52, v51
	s_nop 1
	v_permlane16_swap_b32_e32 v52, v52
	v_rsq_f32_e32 v49, v49
	v_rcp_f32_e32 v55, v55
	v_add_f32_e32 v50, 1.0, v50
	v_rcp_f32_e32 v50, v50
	s_waitcnt lgkmcnt(0)
	v_add_f32_e32 v51, v51, v52
	v_mov_b32_e32 v52, v51
	s_nop 1
	v_permlane32_swap_b32_e32 v52, v52
	v_mul_f32_e32 v53, 0x45800000, v49
	v_cndmask_b32_e32 v49, v49, v53, vcc
	v_mul_f32_e32 v48, v49, v48
	v_mul_f32_e32 v49, v50, v113
	v_fma_mixlo_f16 v48, v49, v48, 0
	global_store_short v[14:15], v48, off offset:1536
	s_waitcnt lgkmcnt(0)
	v_add_f32_e32 v14, v51, v52
	v_sub_f32_e32 v15, v111, v94
	v_add_f32_e32 v48, -1.0, v114
	v_fma_mix_f32 v13, v14, s84, v13 op_sel_hi:[0,0,1]
	v_sub_f32_e32 v14, v112, v95
	v_fma_mix_f32 v15, v76, v15, v105 op_sel_hi:[0,0,1]
	v_fma_f32 v48, v74, v48, 1.0
	v_fma_mix_f32 v14, v75, v14, v104 op_sel_hi:[0,0,1]
	v_mul_f32_e32 v15, v15, v48
	v_mul_f32_e32 v48, v14, v15
	v_mul_f32_e32 v14, v73, v48
	v_mov_b32_e32 v49, 0
	v_cvt_f32_f16_e32 v15, v106
	v_mov_b32_e32 v51, 0
	v_mov_b32_dpp v49, v14 row_ror:8 row_mask:0xf bank_mask:0xf
	v_cvt_f32_f16_e32 v14, v107
	v_fmac_f32_e32 v49, v73, v48
	v_mov_b32_e32 v50, 0
	v_sub_f32_e32 v52, v110, v92
	v_add_f32_dpp v48, v49, v49 row_ror:4 row_mask:0xf bank_mask:0xf bound_ctrl:1
	v_fma_mix_f32 v52, v77, v52, v100 op_sel_hi:[0,0,1]
	s_nop 0
	v_add_f32_dpp v53, v48, v48 row_ror:2 row_mask:0xf bank_mask:0xf bound_ctrl:1
	v_pk_mul_f32 v[48:49], v[14:15], v[14:15]
	s_nop 0
	v_add_f32_dpp v53, v53, v53 row_ror:1 row_mask:0xf bank_mask:0xf bound_ctrl:1
	v_mov_b32_dpp v51, v49 row_ror:8 row_mask:0xf bank_mask:0xf
	v_mov_b32_dpp v50, v48 row_ror:8 row_mask:0xf bank_mask:0xf
	v_pk_fma_f32 v[48:49], v[14:15], v[14:15], v[50:51]
	v_mov_b32_e32 v51, 0
	v_mov_b32_e32 v50, 0
	v_mov_b32_e32 v54, v53
	s_nop 1
	v_permlane16_swap_b32_e32 v54, v54
	v_mov_b32_dpp v51, v49 row_ror:4 row_mask:0xf bank_mask:0xf
	v_mov_b32_dpp v50, v48 row_ror:4 row_mask:0xf bank_mask:0xf
	v_pk_add_f32 v[48:49], v[48:49], v[50:51]
	v_mov_b32_e32 v51, 0
	v_mov_b32_e32 v50, 0
	s_waitcnt lgkmcnt(0)
	v_add_f32_e32 v53, v53, v54
	v_mov_b32_dpp v51, v49 row_ror:2 row_mask:0xf bank_mask:0xf
	v_mov_b32_dpp v50, v48 row_ror:2 row_mask:0xf bank_mask:0xf
	v_pk_add_f32 v[48:49], v[48:49], v[50:51]
	v_mov_b32_e32 v51, 0
	v_mov_b32_e32 v50, 0
	v_mov_b32_e32 v54, v53
	s_nop 1
	v_permlane32_swap_b32_e32 v54, v54
	v_mov_b32_dpp v51, v49 row_ror:1 row_mask:0xf bank_mask:0xf
	v_mov_b32_dpp v50, v48 row_ror:1 row_mask:0xf bank_mask:0xf
	v_pk_add_f32 v[48:49], v[48:49], v[50:51]
	v_mov_b32_e32 v51, v49
	s_nop 1
	v_permlane16_swap_b32_e32 v51, v51
	v_mov_b32_e32 v50, v48
	s_nop 1
	v_permlane16_swap_b32_e32 v50, v50
	s_waitcnt lgkmcnt(2)
	v_add_f32_e32 v53, v53, v54
	s_waitcnt lgkmcnt(0)
	v_pk_add_f32 v[48:49], v[48:49], v[50:51]
	v_mov_b32_e32 v51, v49
	s_nop 1
	v_permlane32_swap_b32_e32 v51, v51
	v_mov_b32_e32 v50, v48
	s_nop 1
	v_permlane32_swap_b32_e32 v50, v50
	s_waitcnt lgkmcnt(0)
	v_pk_add_f32 v[48:49], v[48:49], v[50:51]
	s_nop 0
	v_pk_fma_f32 v[48:49], v[48:49], s[6:7], v[0:1] op_sel_hi:[1,0,0]
	s_nop 0
	v_mul_f32_e32 v50, 0x4b800000, v49
	v_cmp_gt_f32_e32 vcc, s85, v49
	s_nop 1
	v_cndmask_b32_e32 v49, v49, v50, vcc
	v_rsq_f32_e32 v49, v49
	v_mul_f32_e32 v50, v55, v108
	v_mul_f32_e32 v51, 0x45800000, v49
	v_cndmask_b32_e32 v49, v49, v51, vcc
	v_mul_f32_e32 v15, v49, v15
	v_mul_f32_e32 v49, 0x4b800000, v48
	v_cmp_gt_f32_e32 vcc, s85, v48
	v_mul_f32_e32 v15, v17, v15
	v_fma_mixlo_f16 v15, v50, v15, 0
	v_cndmask_b32_e32 v48, v48, v49, vcc
	v_rsq_f32_e32 v54, v48
	v_mul_f32_e32 v48, 0xbfb8aa3b, v103
	v_exp_f32_e32 v55, v48
	v_pk_mul_f32 v[48:49], v[12:13], v[12:13]
	v_mov_b32_e32 v50, 0
	v_mov_b32_e32 v51, 0
	global_store_short v[10:11], v15, off
	v_mov_b32_dpp v50, v48 row_ror:8 row_mask:0xf bank_mask:0xf
	v_mov_b32_dpp v51, v49 row_ror:8 row_mask:0xf bank_mask:0xf
	v_pk_fma_f32 v[48:49], v[12:13], v[12:13], v[50:51]
	v_mov_b32_e32 v50, 0
	v_mov_b32_e32 v51, 0
	v_mul_f32_e32 v15, 0x45800000, v54
	v_mov_b32_dpp v50, v48 row_ror:4 row_mask:0xf bank_mask:0xf
	v_mov_b32_dpp v51, v49 row_ror:4 row_mask:0xf bank_mask:0xf
	v_pk_add_f32 v[48:49], v[48:49], v[50:51]
	v_mov_b32_e32 v50, 0
	v_mov_b32_e32 v51, 0
	v_cndmask_b32_e32 v15, v54, v15, vcc
	v_mov_b32_dpp v50, v48 row_ror:2 row_mask:0xf bank_mask:0xf
	v_mov_b32_dpp v51, v49 row_ror:2 row_mask:0xf bank_mask:0xf
	v_pk_add_f32 v[48:49], v[48:49], v[50:51]
	v_mov_b32_e32 v50, 0
	v_mov_b32_e32 v51, 0
	v_mul_f32_e32 v14, v15, v14
	v_mov_b32_dpp v50, v48 row_ror:1 row_mask:0xf bank_mask:0xf
	v_mov_b32_dpp v51, v49 row_ror:1 row_mask:0xf bank_mask:0xf
	v_pk_add_f32 v[48:49], v[48:49], v[50:51]
	v_mov_b32_e32 v50, v48
	s_nop 1
	v_permlane16_swap_b32_e32 v50, v50
	v_mov_b32_e32 v51, v49
	s_nop 1
	v_permlane16_swap_b32_e32 v51, v51
	v_mul_f32_e32 v54, v70, v14
	v_add_f32_e32 v55, 1.0, v55
	v_rcp_f32_e32 v55, v55
	s_waitcnt lgkmcnt(0)
	v_pk_add_f32 v[48:49], v[48:49], v[50:51]
	v_mov_b32_e32 v50, v48
	s_nop 1
	v_permlane32_swap_b32_e32 v50, v50
	v_mov_b32_e32 v51, v49
	s_nop 1
	v_permlane32_swap_b32_e32 v51, v51
	v_mul_f32_e32 v55, v55, v103
	s_waitcnt lgkmcnt(0)
	v_pk_add_f32 v[14:15], v[48:49], v[50:51]
	s_nop 0
	v_pk_fma_f32 v[14:15], v[14:15], s[6:7], v[2:3] op_sel_hi:[1,0,1]
	v_mul_f32_e32 v51, 0xbfb8aa3b, v90
	v_mul_f32_e32 v48, 0x4b800000, v15
	v_cmp_gt_f32_e32 vcc, s85, v15
	v_exp_f32_e32 v51, v51
	s_nop 0
	v_cndmask_b32_e32 v15, v15, v48, vcc
	v_rsq_f32_e32 v15, v15
	v_fma_mixlo_f16 v48, v55, v54, 0
	global_store_short v[10:11], v48, off offset:512
	ds_read2st64_b32 v[48:49], v4 offset0:56 offset1:60
	v_mul_f32_e32 v4, 0x45800000, v15
	v_cndmask_b32_e32 v4, v15, v4, vcc
	v_mul_f32_e32 v4, v13, v4
	v_fma_f32 v4, v71, v4, v72
	v_fmac_f32_e32 v4, v52, v53
	s_waitcnt lgkmcnt(0)
	v_fma_mixlo_f16 v4, v48, v4, 0
	global_store_short v[10:11], v4, off offset:1024
	v_mul_f32_e32 v4, 0x4b800000, v14
	v_cmp_gt_f32_e32 vcc, s85, v14
	v_mul_f32_e32 v13, 0xbfb8aa3b, v98
	v_exp_f32_e32 v13, v13
	v_cndmask_b32_e32 v4, v14, v4, vcc
	v_add_f32_dpp v14, v102, v102 row_ror:8 row_mask:0xf bank_mask:0xf bound_ctrl:1
	v_rsq_f32_e32 v4, v4
	v_add_f32_e32 v13, 1.0, v13
	v_add_f32_dpp v14, v14, v14 row_ror:4 row_mask:0xf bank_mask:0xf bound_ctrl:1
	v_rcp_f32_e32 v13, v13
	v_mul_f32_e32 v48, 0x45800000, v4
	v_add_f32_dpp v14, v14, v14 row_ror:2 row_mask:0xf bank_mask:0xf bound_ctrl:1
	v_cndmask_b32_e32 v4, v4, v48, vcc
	v_mul_f32_e32 v4, v4, v12
	v_add_f32_dpp v14, v14, v14 row_ror:1 row_mask:0xf bank_mask:0xf bound_ctrl:1
	v_mov_b32_e32 v15, v14
	s_nop 1
	v_permlane16_swap_b32_e32 v15, v15
	v_mul_f32_e32 v12, v13, v98
	v_fma_mixlo_f16 v4, v12, v4, 0
	global_store_short v[10:11], v4, off offset:1536
	v_sub_f32_e32 v10, v94, v99
	s_waitcnt lgkmcnt(0)
	v_add_f32_e32 v14, v14, v15
	v_mov_b32_e32 v15, v14
	s_nop 1
	v_permlane32_swap_b32_e32 v15, v15
	v_add_f32_e32 v11, -1.0, v93
	v_fma_mix_f32 v10, v76, v10, v88 op_sel_hi:[0,0,1]
	v_fma_f32 v11, v74, v11, 1.0
	v_mul_f32_e32 v10, v11, v10
	s_waitcnt lgkmcnt(0)
	v_add_f32_e32 v4, v14, v15
	v_fma_mix_f32 v9, v4, s84, v9 op_sel_hi:[0,0,1]
	v_sub_f32_e32 v4, v95, v101
	v_fma_mix_f32 v4, v75, v4, v89 op_sel_hi:[0,0,1]
	v_mul_f32_e32 v4, v4, v10
	v_mul_f32_e32 v10, v73, v4
	v_mov_b32_e32 v12, 0
	s_waitcnt vmcnt(21)
	v_cvt_f32_f16_e32 v11, v96
	v_mov_b32_e32 v15, 0
	v_mov_b32_dpp v12, v10 row_ror:8 row_mask:0xf bank_mask:0xf
	s_waitcnt vmcnt(20)
	v_cvt_f32_f16_e32 v10, v91
	v_fmac_f32_e32 v12, v73, v4
	v_mov_b32_e32 v14, 0
	v_add_f32_e32 v51, 1.0, v51
	v_add_f32_dpp v4, v12, v12 row_ror:4 row_mask:0xf bank_mask:0xf bound_ctrl:1
	v_pk_mul_f32 v[12:13], v[10:11], v[10:11]
	v_rcp_f32_e32 v51, v51
	v_add_f32_dpp v4, v4, v4 row_ror:2 row_mask:0xf bank_mask:0xf bound_ctrl:1
	v_mov_b32_dpp v15, v13 row_ror:8 row_mask:0xf bank_mask:0xf
	v_mov_b32_dpp v14, v12 row_ror:8 row_mask:0xf bank_mask:0xf
	v_pk_fma_f32 v[12:13], v[10:11], v[10:11], v[14:15]
	v_mov_b32_e32 v15, 0
	v_mov_b32_e32 v14, 0
	v_add_f32_dpp v4, v4, v4 row_ror:1 row_mask:0xf bank_mask:0xf bound_ctrl:1
	v_mov_b32_dpp v15, v13 row_ror:4 row_mask:0xf bank_mask:0xf
	v_mov_b32_dpp v14, v12 row_ror:4 row_mask:0xf bank_mask:0xf
	v_pk_add_f32 v[12:13], v[12:13], v[14:15]
	v_mov_b32_e32 v15, 0
	v_mov_b32_e32 v14, 0
	v_mov_b32_e32 v50, v4
	s_nop 1
	v_permlane16_swap_b32_e32 v50, v50
	v_mov_b32_dpp v15, v13 row_ror:2 row_mask:0xf bank_mask:0xf
	v_mov_b32_dpp v14, v12 row_ror:2 row_mask:0xf bank_mask:0xf
	v_pk_add_f32 v[12:13], v[12:13], v[14:15]
	v_mov_b32_e32 v15, 0
	v_mov_b32_e32 v14, 0
	s_waitcnt lgkmcnt(0)
	v_add_f32_e32 v4, v4, v50
	v_mov_b32_dpp v15, v13 row_ror:1 row_mask:0xf bank_mask:0xf
	v_mov_b32_dpp v14, v12 row_ror:1 row_mask:0xf bank_mask:0xf
	v_pk_add_f32 v[12:13], v[12:13], v[14:15]
	v_mov_b32_e32 v15, v13
	s_nop 1
	v_permlane16_swap_b32_e32 v15, v15
	v_mov_b32_e32 v14, v12
	s_nop 1
	v_permlane16_swap_b32_e32 v14, v14
	v_mov_b32_e32 v50, v4
	s_nop 1
	v_permlane32_swap_b32_e32 v50, v50
	v_sub_f32_e32 v48, v92, v97
	s_waitcnt lgkmcnt(1)
	v_pk_add_f32 v[12:13], v[12:13], v[14:15]
	v_mov_b32_e32 v15, v13
	s_nop 1
	v_permlane32_swap_b32_e32 v15, v15
	v_mov_b32_e32 v14, v12
	s_nop 1
	v_permlane32_swap_b32_e32 v14, v14
	s_waitcnt lgkmcnt(2)
	v_add_f32_e32 v4, v4, v50
	s_waitcnt lgkmcnt(0)
	v_pk_add_f32 v[12:13], v[12:13], v[14:15]
	s_nop 0
	v_pk_fma_f32 v[0:1], v[12:13], s[6:7], v[0:1] op_sel_hi:[1,0,0]
	v_fma_mix_f32 v14, v77, v48, v18 op_sel_hi:[0,0,1]
	v_mul_f32_e32 v12, 0x4b800000, v1
	v_cmp_gt_f32_e32 vcc, s85, v1
	s_nop 1
	v_cndmask_b32_e32 v1, v1, v12, vcc
	v_rsq_f32_e32 v1, v1
	v_mul_f32_e32 v12, v51, v90
	v_mul_f32_e32 v13, 0x45800000, v1
	v_cndmask_b32_e32 v1, v1, v13, vcc
	v_mul_f32_e32 v1, v1, v11
	v_mul_f32_e32 v1, v17, v1
	v_fma_mixlo_f16 v1, v12, v1, 0
	global_store_short v[6:7], v1, off
	v_mul_f32_e32 v1, 0x4b800000, v0
	v_cmp_gt_f32_e32 vcc, s85, v0
	v_mov_b32_e32 v12, 0
	v_mov_b32_e32 v13, 0
	v_cndmask_b32_e32 v0, v0, v1, vcc
	v_rsq_f32_e32 v11, v0
	v_pk_mul_f32 v[0:1], v[8:9], v[8:9]
	v_mul_f32_e32 v15, 0x45800000, v11
	s_nop 0
	v_mov_b32_dpp v12, v0 row_ror:8 row_mask:0xf bank_mask:0xf
	v_mov_b32_dpp v13, v1 row_ror:8 row_mask:0xf bank_mask:0xf
	v_pk_fma_f32 v[0:1], v[8:9], v[8:9], v[12:13]
	v_mov_b32_e32 v12, 0
	v_mov_b32_e32 v13, 0
	v_cndmask_b32_e32 v11, v11, v15, vcc
	v_mov_b32_dpp v12, v0 row_ror:4 row_mask:0xf bank_mask:0xf
	v_mov_b32_dpp v13, v1 row_ror:4 row_mask:0xf bank_mask:0xf
	v_pk_add_f32 v[0:1], v[0:1], v[12:13]
	v_mov_b32_e32 v12, 0
	v_mov_b32_e32 v13, 0
	v_mul_f32_e32 v15, 0xbfb8aa3b, v87
	v_mov_b32_dpp v12, v0 row_ror:2 row_mask:0xf bank_mask:0xf
	v_mov_b32_dpp v13, v1 row_ror:2 row_mask:0xf bank_mask:0xf
	v_pk_add_f32 v[0:1], v[0:1], v[12:13]
	v_mov_b32_e32 v12, 0
	v_mov_b32_e32 v13, 0
	v_exp_f32_e32 v15, v15
	v_mov_b32_dpp v12, v0 row_ror:1 row_mask:0xf bank_mask:0xf
	v_mov_b32_dpp v13, v1 row_ror:1 row_mask:0xf bank_mask:0xf
	v_pk_add_f32 v[0:1], v[0:1], v[12:13]
	v_mov_b32_e32 v12, v0
	s_nop 1
	v_permlane16_swap_b32_e32 v12, v12
	v_mov_b32_e32 v13, v1
	s_nop 1
	v_permlane16_swap_b32_e32 v13, v13
	v_mul_f32_e32 v10, v11, v10
	v_add_f32_e32 v11, 1.0, v15
	v_rcp_f32_e32 v11, v11
	v_mul_f32_e32 v10, v70, v10
	s_waitcnt lgkmcnt(0)
	v_pk_add_f32 v[0:1], v[0:1], v[12:13]
	v_mov_b32_e32 v12, v0
	s_nop 1
	v_permlane32_swap_b32_e32 v12, v12
	v_mov_b32_e32 v13, v1
	s_nop 1
	v_permlane32_swap_b32_e32 v13, v13
	s_waitcnt lgkmcnt(0)
	v_pk_add_f32 v[0:1], v[0:1], v[12:13]
	s_nop 0
	v_pk_fma_f32 v[0:1], v[0:1], s[6:7], v[2:3] op_sel_hi:[1,0,1]
	v_mul_f32_e32 v3, 0xbfb8aa3b, v5
	v_mul_f32_e32 v2, 0x4b800000, v1
	v_cmp_gt_f32_e32 vcc, s85, v1
	v_exp_f32_e32 v3, v3
	s_nop 0
	v_cndmask_b32_e32 v1, v1, v2, vcc
	v_rsq_f32_e32 v1, v1
	v_mul_f32_e32 v2, v11, v87
	v_fma_mixlo_f16 v2, v2, v10, 0
	global_store_short v[6:7], v2, off offset:512
	v_mul_f32_e32 v2, 0x45800000, v1
	v_cndmask_b32_e32 v1, v1, v2, vcc
	v_mul_f32_e32 v1, v9, v1
	v_fma_f32 v1, v71, v1, v72
	v_mul_f32_e32 v2, 0x4b800000, v0
	v_cmp_gt_f32_e32 vcc, s85, v0
	v_fmac_f32_e32 v1, v14, v4
	v_fma_mixlo_f16 v1, v49, v1, 0
	v_cndmask_b32_e32 v0, v0, v2, vcc
	v_rsq_f32_e32 v0, v0
	global_store_short v[6:7], v1, off offset:1024
	v_add_f32_e32 v1, 1.0, v3
	v_rcp_f32_e32 v1, v1
	v_mul_f32_e32 v2, 0x45800000, v0
	v_cndmask_b32_e32 v0, v0, v2, vcc
	v_mul_f32_e32 v0, v0, v8
	v_mul_f32_e32 v1, v1, v5
	v_fma_mixlo_f16 v0, v1, v0, 0
	s_and_b64 vcc, exec, s[0:1]
	global_store_short v[6:7], v0, off offset:1536
	s_cbranch_vccnz .LBB0_529

.LBB0_1520:
	s_xor_b64 s[0:1], s[12:13], -1
	s_or_b32 s12, s10, 1
	s_ashr_i32 s13, s12, 31
	s_mul_i32 s11, s12, 0x1e20
	s_mul_hi_i32 s4, s12, 0x1e20
	s_add_u32 s26, s42, s11
	s_addc_u32 s27, s43, s4
	s_lshl_b64 s[34:35], s[12:13], 11
	v_lshl_add_u64 v[60:61], v[36:37], 0, s[34:35]
	v_lshl_add_u64 v[6:7], s[26:27], 0, v[34:35]
	s_lshl_b64 s[12:13], s[12:13], 10
	global_load_ushort v161, v[60:61], off
	global_load_ushort v162, v[60:61], off offset:512
	global_load_ushort v67, v[60:61], off offset:1024
	global_load_ushort v1, v[60:61], off offset:1536
	v_add_co_u32_e32 v8, vcc, s16, v6
	v_lshl_add_u64 v[10:11], v[38:39], 0, s[12:13]
	s_nop 0
	v_addc_co_u32_e32 v9, vcc, 0, v7, vcc
	global_load_ushort v3, v[10:11], off offset:512
	v_lshl_add_u64 v[10:11], v[16:17], 1, s[26:27]
	s_or_b32 s12, s10, 2
	v_add_co_u32_e32 v10, vcc, s17, v10
	s_ashr_i32 s13, s12, 31
	s_nop 0
	v_addc_co_u32_e32 v11, vcc, -1, v11, vcc
	s_lshl_b64 s[26:27], s[12:13], 11
	global_load_ushort v5, v[10:11], off offset:-3616
	global_load_ushort v94, v[6:7], off offset:1536
	global_load_ushort v95, v[6:7], off offset:3072
	global_load_ushort v96, v[8:9], off offset:3072
	global_load_ushort v166, v[6:7], off offset:3584
	global_load_ushort v165, v[8:9], off offset:128
	global_load_ushort v160, v[8:9], off offset:640
	global_load_ushort v97, v[6:7], off offset:-3488
	global_load_ushort v98, v[6:7], off offset:-2976
	v_lshl_add_u64 v[56:57], v[36:37], 0, s[26:27]
	v_mad_i64_i32 v[6:7], s[26:27], s12, v86, v[42:43]
	v_add_co_u32_e32 v8, vcc, s16, v6
	s_lshl_b64 s[12:13], s[12:13], 10
	global_load_ushort v149, v[56:57], off
	global_load_ushort v150, v[56:57], off offset:512
	global_load_ushort v65, v[56:57], off offset:1024
	global_load_ushort v99, v[56:57], off offset:1536
	v_addc_co_u32_e32 v9, vcc, 0, v7, vcc
	global_load_ushort v101, v[6:7], off offset:1536
	global_load_ushort v102, v[6:7], off offset:3072
	global_load_ushort v103, v[8:9], off offset:3072
	global_load_ushort v151, v[6:7], off offset:3584
	global_load_ushort v152, v[8:9], off offset:128
	global_load_ushort v147, v[8:9], off offset:640
	v_lshl_add_u64 v[6:7], v[38:39], 0, s[12:13]
	s_or_b32 s12, s10, 3
	s_ashr_i32 s13, s12, 31
	s_lshl_b64 s[26:27], s[12:13], 11
	global_load_ushort v108, v[6:7], off offset:512
	v_lshl_add_u64 v[52:53], v[36:37], 0, s[26:27]
	v_mad_i64_i32 v[6:7], s[26:27], s12, v86, v[42:43]
	v_add_co_u32_e32 v8, vcc, s16, v6
	s_lshl_b64 s[12:13], s[12:13], 10
	global_load_ushort v136, v[52:53], off
	global_load_ushort v137, v[52:53], off offset:512
	global_load_ushort v59, v[52:53], off offset:1024
	global_load_ushort v110, v[52:53], off offset:1536
	v_addc_co_u32_e32 v9, vcc, 0, v7, vcc
	global_load_ushort v111, v[6:7], off offset:1536
	global_load_ushort v112, v[6:7], off offset:3072
	global_load_ushort v113, v[8:9], off offset:3072
	global_load_ushort v143, v[6:7], off offset:3584
	global_load_ushort v144, v[8:9], off offset:128
	global_load_ushort v135, v[8:9], off offset:640
	v_lshl_add_u64 v[6:7], v[38:39], 0, s[12:13]
	s_or_b32 s12, s10, 4
	s_ashr_i32 s13, s12, 31
	s_lshl_b64 s[26:27], s[12:13], 11
	global_load_ushort v114, v[6:7], off offset:512
	v_lshl_add_u64 v[50:51], v[36:37], 0, s[26:27]
	v_mad_i64_i32 v[6:7], s[26:27], s12, v86, v[42:43]
	v_add_co_u32_e32 v8, vcc, s16, v6
	s_lshl_b64 s[12:13], s[12:13], 10
	global_load_ushort v123, v[50:51], off
	global_load_ushort v124, v[50:51], off offset:512
	global_load_ushort v55, v[50:51], off offset:1024
	global_load_ushort v115, v[50:51], off offset:1536
	v_addc_co_u32_e32 v9, vcc, 0, v7, vcc
	global_load_ushort v116, v[6:7], off offset:1536
	global_load_ushort v119, v[6:7], off offset:3072
	global_load_ushort v125, v[8:9], off offset:3072
	global_load_ushort v131, v[6:7], off offset:3584
	global_load_ushort v132, v[8:9], off offset:128
	global_load_ushort v122, v[8:9], off offset:640
	v_lshl_add_u64 v[6:7], v[38:39], 0, s[12:13]
	s_or_b32 s12, s10, 5
	s_ashr_i32 s13, s12, 31
	s_lshl_b64 s[26:27], s[12:13], 11
	global_load_ushort v129, v[6:7], off offset:512
	v_lshl_add_u64 v[46:47], v[36:37], 0, s[26:27]
	v_mad_i64_i32 v[6:7], s[26:27], s12, v86, v[42:43]
	v_add_co_u32_e32 v8, vcc, s16, v6
	s_lshl_b64 s[12:13], s[12:13], 10
	global_load_ushort v49, v[46:47], off offset:1024
	global_load_ushort v169, v[46:47], off offset:1536
	v_addc_co_u32_e32 v9, vcc, 0, v7, vcc
	global_load_ushort v172, v[6:7], off offset:1536
	global_load_ushort v173, v[6:7], off offset:3072
	global_load_ushort v176, v[8:9], off offset:3072
	global_load_ushort v117, v[6:7], off offset:3584
	global_load_ushort v118, v[8:9], off offset:128
	global_load_ushort v109, v[8:9], off offset:640
	v_lshl_add_u64 v[6:7], v[38:39], 0, s[12:13]
	global_load_ushort v177, v[6:7], off offset:512
	v_cvt_f32_f16_e32 v185, v69
	s_waitcnt vmcnt(60)
	v_cvt_f32_f16_e32 v187, v66
	s_waitcnt vmcnt(57)
	v_cvt_f32_f16_e32 v190, v167
	v_cvt_f32_f16_e32 v192, v58
	v_cvt_f32_f16_e32 v189, v168
	v_cvt_f32_f16_e32 v171, v48
	v_cvt_f32_f16_e32 v170, v54
	s_waitcnt vmcnt(52)
	v_cvt_f32_f16_e32 v66, v1
	v_add_f32_dpp v1, v185, v185 row_ror:8 row_mask:0xf bank_mask:0xf bound_ctrl:1
	v_sub_f32_e32 v0, v0, v189
	v_fma_mix_f32 v0, v75, v0, v168 op_sel_hi:[0,0,1]
	v_add_f32_dpp v1, v1, v1 row_ror:4 row_mask:0xf bank_mask:0xf bound_ctrl:1
	s_or_b32 s12, s10, 6
	s_waitcnt vmcnt(51)
	v_cvt_f32_f16_e32 v200, v3
	v_add_f32_dpp v1, v1, v1 row_ror:2 row_mask:0xf bank_mask:0xf bound_ctrl:1
	s_ashr_i32 s13, s12, 31
	s_lshl_b64 s[26:27], s[12:13], 11
	v_add_f32_dpp v1, v1, v1 row_ror:1 row_mask:0xf bank_mask:0xf bound_ctrl:1
	v_mov_b32_e32 v3, v1
	s_nop 1
	v_permlane16_swap_b32_e32 v3, v3
	v_lshl_add_u64 v[10:11], v[36:37], 0, s[26:27]
	v_mad_i64_i32 v[6:7], s[26:27], s12, v86, v[42:43]
	v_add_co_u32_e32 v8, vcc, s16, v6
	s_waitcnt lgkmcnt(0)
	v_add_f32_e32 v1, v1, v3
	v_mov_b32_e32 v3, v1
	s_nop 1
	v_permlane32_swap_b32_e32 v3, v3
	s_lshl_b64 s[12:13], s[12:13], 10
	s_or_b32 s10, s10, 7
	global_load_ushort v45, v[10:11], off offset:1024
	global_load_ushort v178, v[10:11], off offset:1536
	v_addc_co_u32_e32 v9, vcc, 0, v7, vcc
	s_waitcnt lgkmcnt(0)
	v_add_f32_e32 v1, v1, v3
	v_fma_mix_f32 v69, v1, s18, v69 op_sel_hi:[0,0,1]
	v_sub_f32_e32 v1, v2, v190
	v_add_f32_e32 v2, -1.0, v192
	v_fma_mix_f32 v1, v76, v1, v167 op_sel_hi:[0,0,1]
	v_fma_f32 v2, v74, v2, 1.0
	v_mul_f32_e32 v1, v2, v1
	v_mul_f32_e32 v0, v0, v1
	v_mul_f32_e32 v1, v73, v0
	v_mov_b32_e32 v2, 0
	v_mov_b32_e32 v3, 0
	global_load_ushort v179, v[6:7], off offset:1536
	global_load_ushort v180, v[6:7], off offset:3072
	global_load_ushort v181, v[8:9], off offset:3072
	global_load_ushort v104, v[6:7], off offset:3584
	global_load_ushort v105, v[8:9], off offset:128
	global_load_ushort v100, v[8:9], off offset:640
	v_mov_b32_dpp v2, v1 row_ror:8 row_mask:0xf bank_mask:0xf
	s_waitcnt vmcnt(32)
	v_cvt_f32_f16_e32 v141, v113
	v_fmac_f32_e32 v2, v73, v0
	v_lshl_add_u64 v[6:7], v[38:39], 0, s[12:13]
	s_ashr_i32 s11, s10, 31
	v_add_f32_dpp v0, v2, v2 row_ror:4 row_mask:0xf bank_mask:0xf bound_ctrl:1
	v_mov_b32_e32 v2, 0
	s_mul_i32 s12, s10, 0x1e20
	v_add_f32_dpp v167, v0, v0 row_ror:2 row_mask:0xf bank_mask:0xf bound_ctrl:1
	s_mul_hi_i32 s4, s10, 0x1e20
	s_add_u32 s12, s42, s12
	v_add_f32_dpp v167, v167, v167 row_ror:1 row_mask:0xf bank_mask:0xf bound_ctrl:1
	v_cvt_f32_f16_e32 v186, v64
	v_mov_b32_e32 v168, v167
	s_nop 1
	v_permlane16_swap_b32_e32 v168, v168
	s_waitcnt vmcnt(23)
	v_cvt_f32_f16_e32 v134, v116
	s_waitcnt vmcnt(22)
	v_cvt_f32_f16_e32 v133, v119
	s_addc_u32 s13, s43, s4
	v_lshl_add_u64 v[90:91], s[12:13], 0, v[34:35]
	v_add_co_u32_e32 v92, vcc, s16, v90
	s_waitcnt lgkmcnt(0)
	v_add_f32_e32 v167, v167, v168
	v_addc_co_u32_e32 v93, vcc, 0, v91, vcc
	v_mov_b32_e32 v168, v167
	s_nop 1
	v_permlane32_swap_b32_e32 v168, v168
	s_waitcnt vmcnt(17)
	v_cvt_f32_f16_e32 v142, v129
	v_cvt_f32_f16_e32 v191, v164
	s_lshl_b64 s[26:27], s[10:11], 10
	v_lshl_add_u64 v[8:9], v[38:39], 0, s[26:27]
	s_waitcnt lgkmcnt(0)
	v_add_f32_e32 v167, v167, v168
	s_waitcnt vmcnt(14)
	v_cvt_f32_f16_e32 v119, v172
	s_waitcnt vmcnt(13)
	v_cvt_f32_f16_e32 v116, v173
	s_waitcnt vmcnt(12)
	v_cvt_f32_f16_e32 v113, v176
	v_pk_mul_f32 v[172:173], v[170:171], v[170:171]
	v_mov_b32_e32 v176, 0
	v_cvt_f32_f16_e32 v48, v169
	v_mul_f32_e32 v169, 0xbfb8aa3b, v186
	s_waitcnt vmcnt(8)
	v_cvt_f32_f16_e32 v129, v177
	v_mov_b32_e32 v177, 0
	v_mov_b32_dpp v176, v172 row_ror:8 row_mask:0xf bank_mask:0xf
	v_exp_f32_e32 v169, v169
	v_mov_b32_dpp v177, v173 row_ror:8 row_mask:0xf bank_mask:0xf
	v_pk_fma_f32 v[0:1], v[170:171], v[170:171], v[176:177]
	v_sub_f32_e32 v4, v4, v191
	v_add_f32_e32 v169, 1.0, v169
	v_mov_b32_dpp v3, v1 row_ror:4 row_mask:0xf bank_mask:0xf
	v_mov_b32_dpp v2, v0 row_ror:4 row_mask:0xf bank_mask:0xf
	v_pk_add_f32 v[0:1], v[0:1], v[2:3]
	v_mov_b32_e32 v3, 0
	v_mov_b32_e32 v2, 0
	v_rcp_f32_e32 v169, v169
	v_mov_b32_dpp v3, v1 row_ror:2 row_mask:0xf bank_mask:0xf
	v_mov_b32_dpp v2, v0 row_ror:2 row_mask:0xf bank_mask:0xf
	v_pk_add_f32 v[0:1], v[0:1], v[2:3]
	v_mov_b32_e32 v3, 0
	v_mov_b32_e32 v2, 0
	global_load_ushort v182, v[6:7], off offset:512
	global_load_ushort v183, v[8:9], off offset:512
	v_mov_b32_dpp v3, v1 row_ror:1 row_mask:0xf bank_mask:0xf
	v_mov_b32_dpp v2, v0 row_ror:1 row_mask:0xf bank_mask:0xf
	v_pk_add_f32 v[0:1], v[0:1], v[2:3]
	v_mov_b32_e32 v3, v1
	s_nop 1
	v_permlane16_swap_b32_e32 v3, v3
	v_mov_b32_e32 v2, v0
	s_nop 1
	v_permlane16_swap_b32_e32 v2, v2
	v_lshl_add_u64 v[6:7], v[20:21], 1, s[12:13]
	v_lshl_add_u64 v[8:9], v[18:19], 1, s[12:13]
	s_lshl_b64 s[10:11], s[10:11], 11
	v_fma_mix_f32 v164, v77, v4, v164 op_sel_hi:[0,0,1]
	s_waitcnt lgkmcnt(0)
	v_pk_add_f32 v[0:1], v[0:1], v[2:3]
	v_mov_b32_e32 v3, v1
	s_nop 1
	v_permlane32_swap_b32_e32 v3, v3
	v_mov_b32_e32 v2, v0
	s_nop 1
	v_permlane32_swap_b32_e32 v2, v2
	v_mul_f32_e32 v4, v169, v186
	global_load_ushort v14, v[6:7], off
	global_load_ushort v88, v[8:9], off
	global_load_ushort v89, v[90:91], off offset:3584
	s_nop 0
	global_load_ushort v8, v[92:93], off offset:3072
	global_load_ushort v184, v[90:91], off offset:3072
	s_nop 0
	global_load_ushort v90, v[90:91], off offset:1536
	v_lshl_add_u64 v[6:7], v[36:37], 0, s[10:11]
	v_cvt_f32_f16_e32 v68, v44
	s_waitcnt lgkmcnt(0)
	v_pk_add_f32 v[2:3], v[0:1], v[2:3]
	v_mov_b64_e32 v[0:1], s[8:9]
	v_pk_fma_f32 v[2:3], v[2:3], s[6:7], v[0:1] op_sel_hi:[1,0,0]
	global_load_ushort v91, v[6:7], off offset:1536
	global_load_ushort v120, v[46:47], off
	global_load_ushort v121, v[46:47], off offset:512
	global_load_ushort v106, v[10:11], off
	global_load_ushort v107, v[10:11], off offset:512
	v_mul_f32_e32 v172, 0x4b800000, v3
	v_cmp_gt_f32_e32 vcc, s19, v3
	v_mov_b32_e32 v169, 0
	v_cvt_f32_f16_e32 v193, v67
	v_cndmask_b32_e32 v3, v3, v172, vcc
	v_rsq_f32_e32 v3, v3
	v_cvt_f32_f16_e32 v188, v87
	v_cvt_f32_f16_e32 v198, v165
	v_cvt_f32_f16_e32 v202, v97
	v_mul_f32_e32 v168, 0x45800000, v3
	v_cndmask_b32_e32 v3, v3, v168, vcc
	v_mul_f32_e32 v3, v3, v171
	v_mul_f32_e32 v3, v13, v3
	v_fma_mixlo_f16 v3, v4, v3, 0
	global_store_short v[62:63], v3, off
	v_mul_f32_e32 v3, 0x4b800000, v2
	v_cmp_gt_f32_e32 vcc, s19, v2
	v_mov_b32_e32 v168, 0
	v_cvt_f32_f16_e32 v197, v166
	v_cndmask_b32_e32 v2, v2, v3, vcc
	v_rsq_f32_e32 v4, v2
	v_mul_f32_e32 v2, 0xbfb8aa3b, v187
	v_exp_f32_e32 v171, v2
	v_pk_mul_f32 v[2:3], v[68:69], v[68:69]
	v_mul_f32_e32 v172, 0x45800000, v4
	v_cndmask_b32_e32 v4, v4, v172, vcc
	v_mov_b32_dpp v168, v2 row_ror:8 row_mask:0xf bank_mask:0xf
	v_mov_b32_dpp v169, v3 row_ror:8 row_mask:0xf bank_mask:0xf
	v_pk_fma_f32 v[2:3], v[68:69], v[68:69], v[168:169]
	v_mov_b32_e32 v168, 0
	v_mov_b32_e32 v169, 0
	v_add_f32_e32 v171, 1.0, v171
	v_mov_b32_dpp v168, v2 row_ror:4 row_mask:0xf bank_mask:0xf
	v_mov_b32_dpp v169, v3 row_ror:4 row_mask:0xf bank_mask:0xf
	v_pk_add_f32 v[2:3], v[2:3], v[168:169]
	v_mov_b32_e32 v168, 0
	v_mov_b32_e32 v169, 0
	v_rcp_f32_e32 v171, v171
	v_mov_b32_dpp v168, v2 row_ror:2 row_mask:0xf bank_mask:0xf
	v_mov_b32_dpp v169, v3 row_ror:2 row_mask:0xf bank_mask:0xf
	v_pk_add_f32 v[2:3], v[2:3], v[168:169]
	v_mov_b32_e32 v168, 0
	v_mov_b32_e32 v169, 0
	v_mul_f32_e32 v4, v4, v170
	v_mov_b32_dpp v168, v2 row_ror:1 row_mask:0xf bank_mask:0xf
	v_mov_b32_dpp v169, v3 row_ror:1 row_mask:0xf bank_mask:0xf
	v_pk_add_f32 v[2:3], v[2:3], v[168:169]
	v_mov_b32_e32 v168, v2
	s_nop 1
	v_permlane16_swap_b32_e32 v168, v168
	v_mov_b32_e32 v169, v3
	s_nop 1
	v_permlane16_swap_b32_e32 v169, v169
	v_mul_f32_e32 v4, v70, v4
	v_mul_f32_e32 v170, v171, v187
	v_fma_mixlo_f16 v4, v170, v4, 0
	global_store_short v[62:63], v4, off offset:512
	s_waitcnt lgkmcnt(0)
	v_pk_add_f32 v[2:3], v[2:3], v[168:169]
	v_mov_b32_e32 v168, v2
	s_nop 1
	v_permlane32_swap_b32_e32 v168, v168
	v_mov_b32_e32 v169, v3
	s_nop 1
	v_permlane32_swap_b32_e32 v169, v169
	v_lshl_add_u32 v4, s24, 10, v84
	v_cvt_f32_f16_e32 v201, v5
	v_cvt_f32_f16_e32 v194, v94
	v_cvt_f32_f16_e32 v199, v160
	s_waitcnt lgkmcnt(0)
	v_pk_add_f32 v[168:169], v[2:3], v[168:169]
	v_mov_b64_e32 v[2:3], s[8:9]
	v_pk_fma_f32 v[168:169], v[168:169], s[6:7], v[2:3] op_sel_hi:[1,0,1]
	v_cvt_f32_f16_e32 v203, v98
	v_mul_f32_e32 v170, 0x4b800000, v169
	v_cmp_gt_f32_e32 vcc, s19, v169
	v_cvt_f32_f16_e32 v195, v95
	v_cvt_f32_f16_e32 v204, v65
	v_cndmask_b32_e32 v169, v169, v170, vcc
	v_rsq_f32_e32 v169, v169
	ds_read2st64_b32 v[170:171], v4 offset0:32 offset1:36
	v_cvt_f32_f16_e32 v196, v96
	v_cvt_f32_f16_e32 v154, v152
	v_mul_f32_e32 v172, 0x45800000, v169
	v_cndmask_b32_e32 v169, v169, v172, vcc
	v_mul_f32_e32 v69, v69, v169
	v_fma_f32 v69, v71, v69, v72
	v_fmac_f32_e32 v69, v164, v167
	v_add_f32_dpp v167, v193, v193 row_ror:8 row_mask:0xf bank_mask:0xf bound_ctrl:1
	s_waitcnt lgkmcnt(0)
	v_fma_mixlo_f16 v69, v170, v69, 0
	global_store_short v[62:63], v69, off offset:1024
	v_add_f32_dpp v167, v167, v167 row_ror:4 row_mask:0xf bank_mask:0xf bound_ctrl:1
	v_mul_f32_e32 v69, 0x4b800000, v168
	v_cmp_gt_f32_e32 vcc, s19, v168
	v_add_f32_dpp v167, v167, v167 row_ror:2 row_mask:0xf bank_mask:0xf bound_ctrl:1
	v_mul_f32_e32 v164, 0xbfb8aa3b, v188
	v_cndmask_b32_e32 v69, v168, v69, vcc
	v_add_f32_dpp v167, v167, v167 row_ror:1 row_mask:0xf bank_mask:0xf bound_ctrl:1
	v_exp_f32_e32 v164, v164
	v_mov_b32_e32 v168, v167
	s_nop 1
	v_permlane16_swap_b32_e32 v168, v168
	v_rsq_f32_e32 v69, v69
	v_cvt_f32_f16_e32 v205, v108
	v_add_f32_e32 v164, 1.0, v164
	v_rcp_f32_e32 v164, v164
	s_waitcnt lgkmcnt(0)
	v_add_f32_e32 v167, v167, v168
	v_mov_b32_e32 v168, v167
	s_nop 1
	v_permlane32_swap_b32_e32 v168, v168
	v_mul_f32_e32 v169, 0x45800000, v69
	v_cndmask_b32_e32 v69, v69, v169, vcc
	v_mul_f32_e32 v68, v69, v68
	v_mul_f32_e32 v69, v164, v188
	v_fma_mixlo_f16 v68, v69, v68, 0
	global_store_short v[62:63], v68, off offset:1536
	s_waitcnt lgkmcnt(0)
	v_add_f32_e32 v62, v167, v168
	v_sub_f32_e32 v63, v202, v198
	v_add_f32_e32 v68, -1.0, v200
	v_fma_mix_f32 v67, v62, s18, v67 op_sel_hi:[0,0,1]
	v_sub_f32_e32 v62, v201, v197
	v_fma_mix_f32 v63, v76, v63, v165 op_sel_hi:[0,0,1]
	v_fma_f32 v68, v74, v68, 1.0
	v_fma_mix_f32 v62, v75, v62, v166 op_sel_hi:[0,0,1]
	v_mul_f32_e32 v63, v68, v63
	v_mul_f32_e32 v68, v62, v63
	v_mul_f32_e32 v62, v73, v68
	v_mov_b32_e32 v69, 0
	v_cvt_f32_f16_e32 v63, v161
	v_mov_b32_e32 v165, 0
	v_mov_b32_dpp v69, v62 row_ror:8 row_mask:0xf bank_mask:0xf
	v_cvt_f32_f16_e32 v62, v162
	v_fmac_f32_e32 v69, v73, v68
	v_mov_b32_e32 v164, 0
	v_mul_f32_e32 v167, 0xbfb8aa3b, v194
	v_add_f32_dpp v68, v69, v69 row_ror:4 row_mask:0xf bank_mask:0xf bound_ctrl:1
	v_exp_f32_e32 v167, v167
	v_sub_f32_e32 v166, v203, v199
	v_add_f32_dpp v161, v68, v68 row_ror:2 row_mask:0xf bank_mask:0xf bound_ctrl:1
	v_pk_mul_f32 v[68:69], v[62:63], v[62:63]
	v_add_f32_e32 v167, 1.0, v167
	v_add_f32_dpp v161, v161, v161 row_ror:1 row_mask:0xf bank_mask:0xf bound_ctrl:1
	v_mov_b32_dpp v165, v69 row_ror:8 row_mask:0xf bank_mask:0xf
	v_mov_b32_dpp v164, v68 row_ror:8 row_mask:0xf bank_mask:0xf
	v_pk_fma_f32 v[68:69], v[62:63], v[62:63], v[164:165]
	v_mov_b32_e32 v165, 0
	v_mov_b32_e32 v164, 0
	v_mov_b32_e32 v162, v161
	s_nop 1
	v_permlane16_swap_b32_e32 v162, v162
	v_mov_b32_dpp v165, v69 row_ror:4 row_mask:0xf bank_mask:0xf
	v_mov_b32_dpp v164, v68 row_ror:4 row_mask:0xf bank_mask:0xf
	v_pk_add_f32 v[68:69], v[68:69], v[164:165]
	v_mov_b32_e32 v165, 0
	v_mov_b32_e32 v164, 0
	s_waitcnt lgkmcnt(0)
	v_add_f32_e32 v161, v161, v162
	v_mov_b32_dpp v165, v69 row_ror:2 row_mask:0xf bank_mask:0xf
	v_mov_b32_dpp v164, v68 row_ror:2 row_mask:0xf bank_mask:0xf
	v_pk_add_f32 v[68:69], v[68:69], v[164:165]
	v_mov_b32_e32 v165, 0
	v_mov_b32_e32 v164, 0
	v_mov_b32_e32 v162, v161
	s_nop 1
	v_permlane32_swap_b32_e32 v162, v162
	v_mov_b32_dpp v165, v69 row_ror:1 row_mask:0xf bank_mask:0xf
	v_mov_b32_dpp v164, v68 row_ror:1 row_mask:0xf bank_mask:0xf
	v_pk_add_f32 v[68:69], v[68:69], v[164:165]
	v_mov_b32_e32 v165, v69
	s_nop 1
	v_permlane16_swap_b32_e32 v165, v165
	v_mov_b32_e32 v164, v68
	s_nop 1
	v_permlane16_swap_b32_e32 v164, v164
	v_rcp_f32_e32 v167, v167
	s_waitcnt lgkmcnt(2)
	v_add_f32_e32 v162, v161, v162
	v_cvt_f32_f16_e32 v155, v151
	v_cvt_f32_f16_e32 v163, v101
	s_waitcnt lgkmcnt(0)
	v_pk_add_f32 v[68:69], v[68:69], v[164:165]
	v_mov_b32_e32 v165, v69
	s_nop 1
	v_permlane32_swap_b32_e32 v165, v165
	v_mov_b32_e32 v164, v68
	s_nop 1
	v_permlane32_swap_b32_e32 v164, v164
	v_cvt_f32_f16_e32 v153, v147
	v_cvt_f32_f16_e32 v159, v102
	v_cvt_f32_f16_e32 v64, v99
	v_cvt_f32_f16_e32 v158, v59
	s_waitcnt lgkmcnt(0)
	v_pk_add_f32 v[68:69], v[68:69], v[164:165]
	v_cvt_f32_f16_e32 v156, v103
	v_pk_fma_f32 v[68:69], v[68:69], s[6:7], v[0:1] op_sel_hi:[1,0,0]
	v_cvt_f32_f16_e32 v139, v144
	v_mul_f32_e32 v164, 0x4b800000, v69
	v_cmp_gt_f32_e32 vcc, s19, v69
	v_cvt_f32_f16_e32 v157, v114
	v_cvt_f32_f16_e32 v140, v143
	v_cndmask_b32_e32 v69, v69, v164, vcc
	v_rsq_f32_e32 v69, v69
	v_fma_mix_f32 v164, v77, v166, v160 op_sel_hi:[0,0,1]
	v_mul_f32_e32 v160, v167, v194
	v_cvt_f32_f16_e32 v148, v111
	v_mul_f32_e32 v161, 0x45800000, v69
	v_cndmask_b32_e32 v69, v69, v161, vcc
	v_mul_f32_e32 v63, v69, v63
	v_mul_f32_e32 v63, v13, v63
	v_fma_mixlo_f16 v63, v160, v63, 0
	global_store_short v[60:61], v63, off
	v_mul_f32_e32 v63, 0x4b800000, v68
	v_cmp_gt_f32_e32 vcc, s19, v68
	v_mov_b32_e32 v160, 0
	v_mov_b32_e32 v161, 0
	v_cndmask_b32_e32 v63, v68, v63, vcc
	v_pk_mul_f32 v[68:69], v[66:67], v[66:67]
	v_rsq_f32_e32 v63, v63
	v_cvt_f32_f16_e32 v58, v110
	v_mov_b32_dpp v160, v68 row_ror:8 row_mask:0xf bank_mask:0xf
	v_mov_b32_dpp v161, v69 row_ror:8 row_mask:0xf bank_mask:0xf
	v_pk_fma_f32 v[68:69], v[66:67], v[66:67], v[160:161]
	v_mov_b32_e32 v160, 0
	v_mov_b32_e32 v161, 0
	v_mul_f32_e32 v165, 0x45800000, v63
	v_mov_b32_dpp v160, v68 row_ror:4 row_mask:0xf bank_mask:0xf
	v_mov_b32_dpp v161, v69 row_ror:4 row_mask:0xf bank_mask:0xf
	v_pk_add_f32 v[68:69], v[68:69], v[160:161]
	v_mov_b32_e32 v160, 0
	v_mov_b32_e32 v161, 0
	v_cndmask_b32_e32 v63, v63, v165, vcc
	v_mov_b32_dpp v160, v68 row_ror:2 row_mask:0xf bank_mask:0xf
	v_mov_b32_dpp v161, v69 row_ror:2 row_mask:0xf bank_mask:0xf
	v_pk_add_f32 v[68:69], v[68:69], v[160:161]
	v_mov_b32_e32 v160, 0
	v_mov_b32_e32 v161, 0
	v_mul_f32_e32 v165, 0xbfb8aa3b, v195
	v_mov_b32_dpp v160, v68 row_ror:1 row_mask:0xf bank_mask:0xf
	v_mov_b32_dpp v161, v69 row_ror:1 row_mask:0xf bank_mask:0xf
	v_pk_add_f32 v[68:69], v[68:69], v[160:161]
	v_mov_b32_e32 v160, v68
	s_nop 1
	v_permlane16_swap_b32_e32 v160, v160
	v_mov_b32_e32 v161, v69
	s_nop 1
	v_permlane16_swap_b32_e32 v161, v161
	v_exp_f32_e32 v165, v165
	v_mul_f32_e32 v62, v63, v62
	v_mul_f32_e32 v166, v70, v62
	v_cvt_f32_f16_e32 v146, v112
	s_waitcnt lgkmcnt(0)
	v_pk_add_f32 v[68:69], v[68:69], v[160:161]
	v_mov_b32_e32 v160, v68
	s_nop 1
	v_permlane32_swap_b32_e32 v160, v160
	v_mov_b32_e32 v161, v69
	s_nop 1
	v_permlane32_swap_b32_e32 v161, v161
	v_add_f32_e32 v62, 1.0, v165
	v_rcp_f32_e32 v165, v62
	v_cvt_f32_f16_e32 v138, v135
	v_cvt_f32_f16_e32 v145, v55
	s_waitcnt lgkmcnt(0)
	v_pk_add_f32 v[62:63], v[68:69], v[160:161]
	v_cvt_f32_f16_e32 v126, v132
	v_pk_fma_f32 v[62:63], v[62:63], s[6:7], v[2:3] op_sel_hi:[1,0,1]
	v_cvt_f32_f16_e32 v127, v131
	v_mul_f32_e32 v68, 0x4b800000, v63
	v_cmp_gt_f32_e32 vcc, s19, v63
	v_cvt_f32_f16_e32 v54, v115
	v_cvt_f32_f16_e32 v128, v125
	v_cndmask_b32_e32 v63, v63, v68, vcc
	v_rsq_f32_e32 v63, v63
	v_mul_f32_e32 v68, v165, v195
	v_fma_mixlo_f16 v68, v68, v166, 0
	global_store_short v[60:61], v68, off offset:512
	v_mul_f32_e32 v68, 0x45800000, v63
	v_cndmask_b32_e32 v63, v63, v68, vcc
	v_mul_f32_e32 v63, v67, v63
	v_fma_f32 v63, v71, v63, v72
	v_fmac_f32_e32 v63, v164, v162
	v_add_f32_dpp v67, v204, v204 row_ror:8 row_mask:0xf bank_mask:0xf bound_ctrl:1
	v_fma_mixlo_f16 v63, v171, v63, 0
	global_store_short v[60:61], v63, off offset:1024
	v_add_f32_dpp v67, v67, v67 row_ror:4 row_mask:0xf bank_mask:0xf bound_ctrl:1
	v_mul_f32_e32 v63, 0x4b800000, v62
	v_cmp_gt_f32_e32 vcc, s19, v62
	v_add_f32_dpp v67, v67, v67 row_ror:2 row_mask:0xf bank_mask:0xf bound_ctrl:1
	v_cvt_f32_f16_e32 v125, v122
	v_cndmask_b32_e32 v62, v62, v63, vcc
	v_mul_f32_e32 v63, 0xbfb8aa3b, v196
	v_add_f32_dpp v67, v67, v67 row_ror:1 row_mask:0xf bank_mask:0xf bound_ctrl:1
	v_exp_f32_e32 v63, v63
	v_mov_b32_e32 v68, v67
	s_nop 1
	v_permlane16_swap_b32_e32 v68, v68
	v_rsq_f32_e32 v62, v62
	v_cvt_f32_f16_e32 v130, v49
	v_add_f32_e32 v63, 1.0, v63
	v_rcp_f32_e32 v63, v63
	s_waitcnt lgkmcnt(0)
	v_add_f32_e32 v67, v67, v68
	v_mov_b32_e32 v68, v67
	s_nop 1
	v_permlane32_swap_b32_e32 v68, v68
	v_mul_f32_e32 v69, 0x45800000, v62
	v_cndmask_b32_e32 v62, v62, v69, vcc
	v_mul_f32_e32 v62, v62, v66
	v_mul_f32_e32 v63, v63, v196
	v_fma_mixlo_f16 v62, v63, v62, 0
	global_store_short v[60:61], v62, off offset:1536
	s_waitcnt lgkmcnt(0)
	v_add_f32_e32 v60, v67, v68
	v_sub_f32_e32 v61, v198, v154
	v_add_f32_e32 v62, -1.0, v205
	v_fma_mix_f32 v65, v60, s18, v65 op_sel_hi:[0,0,1]
	v_sub_f32_e32 v60, v197, v155
	v_fma_mix_f32 v61, v76, v61, v152 op_sel_hi:[0,0,1]
	v_fma_f32 v62, v74, v62, 1.0
	v_fma_mix_f32 v60, v75, v60, v151 op_sel_hi:[0,0,1]
	v_mul_f32_e32 v61, v61, v62
	v_mul_f32_e32 v62, v60, v61
	v_mul_f32_e32 v60, v73, v62
	v_mov_b32_e32 v63, 0
	v_cvt_f32_f16_e32 v61, v149
	v_mov_b32_e32 v67, 0
	v_mov_b32_dpp v63, v60 row_ror:8 row_mask:0xf bank_mask:0xf
	v_cvt_f32_f16_e32 v60, v150
	v_fmac_f32_e32 v63, v73, v62
	v_mov_b32_e32 v66, 0
	v_mul_f32_e32 v150, 0xbfb8aa3b, v163
	v_add_f32_dpp v62, v63, v63 row_ror:4 row_mask:0xf bank_mask:0xf bound_ctrl:1
	v_exp_f32_e32 v150, v150
	v_sub_f32_e32 v68, v199, v153
	v_add_f32_dpp v69, v62, v62 row_ror:2 row_mask:0xf bank_mask:0xf bound_ctrl:1
	v_pk_mul_f32 v[62:63], v[60:61], v[60:61]
	v_add_f32_e32 v150, 1.0, v150
	v_add_f32_dpp v69, v69, v69 row_ror:1 row_mask:0xf bank_mask:0xf bound_ctrl:1
	v_mov_b32_dpp v67, v63 row_ror:8 row_mask:0xf bank_mask:0xf
	v_mov_b32_dpp v66, v62 row_ror:8 row_mask:0xf bank_mask:0xf
	v_pk_fma_f32 v[62:63], v[60:61], v[60:61], v[66:67]
	v_mov_b32_e32 v67, 0
	v_mov_b32_e32 v66, 0
	v_mov_b32_e32 v149, v69
	s_nop 1
	v_permlane16_swap_b32_e32 v149, v149
	v_mov_b32_dpp v67, v63 row_ror:4 row_mask:0xf bank_mask:0xf
	v_mov_b32_dpp v66, v62 row_ror:4 row_mask:0xf bank_mask:0xf
	v_pk_add_f32 v[62:63], v[62:63], v[66:67]
	v_mov_b32_e32 v67, 0
	v_mov_b32_e32 v66, 0
	s_waitcnt lgkmcnt(0)
	v_add_f32_e32 v69, v69, v149
	v_mov_b32_dpp v67, v63 row_ror:2 row_mask:0xf bank_mask:0xf
	v_mov_b32_dpp v66, v62 row_ror:2 row_mask:0xf bank_mask:0xf
	v_pk_add_f32 v[62:63], v[62:63], v[66:67]
	v_mov_b32_e32 v67, 0
	v_mov_b32_e32 v66, 0
	v_mov_b32_e32 v149, v69
	s_nop 1
	v_permlane32_swap_b32_e32 v149, v149
	v_mov_b32_dpp v67, v63 row_ror:1 row_mask:0xf bank_mask:0xf
	v_mov_b32_dpp v66, v62 row_ror:1 row_mask:0xf bank_mask:0xf
	v_pk_add_f32 v[62:63], v[62:63], v[66:67]
	v_mov_b32_e32 v67, v63
	s_nop 1
	v_permlane16_swap_b32_e32 v67, v67
	v_mov_b32_e32 v66, v62
	s_nop 1
	v_permlane16_swap_b32_e32 v66, v66
	v_rcp_f32_e32 v150, v150
	v_fma_mix_f32 v68, v77, v68, v147 op_sel_hi:[0,0,1]
	s_waitcnt lgkmcnt(2)
	v_add_f32_e32 v69, v69, v149
	v_cvt_f32_f16_e32 v111, v118
	s_waitcnt lgkmcnt(0)
	v_pk_add_f32 v[62:63], v[62:63], v[66:67]
	v_mov_b32_e32 v67, v63
	s_nop 1
	v_permlane32_swap_b32_e32 v67, v67
	v_mov_b32_e32 v66, v62
	s_nop 1
	v_permlane32_swap_b32_e32 v66, v66
	v_cvt_f32_f16_e32 v112, v117
	v_cvt_f32_f16_e32 v110, v109
	s_waitcnt vmcnt(28)
	v_cvt_f32_f16_e32 v115, v45
	global_load_ushort v9, v[6:7], off offset:1024
	global_load_ushort v96, v[6:7], off
	s_waitcnt lgkmcnt(0)
	v_pk_add_f32 v[62:63], v[62:63], v[66:67]
	s_waitcnt vmcnt(24)
	v_cvt_f32_f16_e32 v94, v105
	v_pk_fma_f32 v[62:63], v[62:63], s[6:7], v[0:1] op_sel_hi:[1,0,0]
	s_waitcnt vmcnt(22)
	v_cvt_f32_f16_e32 v114, v182
	v_mul_f32_e32 v66, 0x4b800000, v63
	v_cmp_gt_f32_e32 vcc, s19, v63
	v_cvt_f32_f16_e32 v95, v104
	s_waitcnt vmcnt(17)
	v_cvt_f32_f16_e32 v5, v8
	v_cndmask_b32_e32 v63, v63, v66, vcc
	v_rsq_f32_e32 v63, v63
	v_mul_f32_e32 v66, v150, v163
	s_waitcnt vmcnt(14)
	v_cvt_f32_f16_e32 v8, v91
	global_load_ushort v91, v[6:7], off offset:512
	v_mul_f32_e32 v67, 0x45800000, v63
	v_cndmask_b32_e32 v63, v63, v67, vcc
	v_mul_f32_e32 v61, v63, v61
	v_mul_f32_e32 v63, 0x4b800000, v62
	v_cmp_gt_f32_e32 vcc, s19, v62
	v_mul_f32_e32 v61, v13, v61
	v_fma_mixlo_f16 v61, v66, v61, 0
	v_cndmask_b32_e32 v62, v62, v63, vcc
	v_rsq_f32_e32 v147, v62
	v_mul_f32_e32 v62, 0xbfb8aa3b, v159
	v_exp_f32_e32 v149, v62
	v_pk_mul_f32 v[62:63], v[64:65], v[64:65]
	v_mov_b32_e32 v66, 0
	v_mov_b32_e32 v67, 0
	global_store_short v[56:57], v61, off
	v_mov_b32_dpp v66, v62 row_ror:8 row_mask:0xf bank_mask:0xf
	v_mov_b32_dpp v67, v63 row_ror:8 row_mask:0xf bank_mask:0xf
	v_pk_fma_f32 v[62:63], v[64:65], v[64:65], v[66:67]
	v_mov_b32_e32 v66, 0
	v_mov_b32_e32 v67, 0
	v_mul_f32_e32 v61, 0x45800000, v147
	v_mov_b32_dpp v66, v62 row_ror:4 row_mask:0xf bank_mask:0xf
	v_mov_b32_dpp v67, v63 row_ror:4 row_mask:0xf bank_mask:0xf
	v_pk_add_f32 v[62:63], v[62:63], v[66:67]
	v_mov_b32_e32 v66, 0
	v_mov_b32_e32 v67, 0
	v_cndmask_b32_e32 v61, v147, v61, vcc
	v_mov_b32_dpp v66, v62 row_ror:2 row_mask:0xf bank_mask:0xf
	v_mov_b32_dpp v67, v63 row_ror:2 row_mask:0xf bank_mask:0xf
	v_pk_add_f32 v[62:63], v[62:63], v[66:67]
	v_mov_b32_e32 v66, 0
	v_mov_b32_e32 v67, 0
	v_mul_f32_e32 v60, v61, v60
	v_mov_b32_dpp v66, v62 row_ror:1 row_mask:0xf bank_mask:0xf
	v_mov_b32_dpp v67, v63 row_ror:1 row_mask:0xf bank_mask:0xf
	v_pk_add_f32 v[62:63], v[62:63], v[66:67]
	v_mov_b32_e32 v66, v62
	s_nop 1
	v_permlane16_swap_b32_e32 v66, v66
	v_mov_b32_e32 v67, v63
	s_nop 1
	v_permlane16_swap_b32_e32 v67, v67
	v_mul_f32_e32 v147, v70, v60
	v_add_f32_e32 v149, 1.0, v149
	v_rcp_f32_e32 v149, v149
	v_cvt_f32_f16_e32 v108, v179
	s_waitcnt lgkmcnt(0)
	v_pk_add_f32 v[62:63], v[62:63], v[66:67]
	v_mov_b32_e32 v66, v62
	s_nop 1
	v_permlane32_swap_b32_e32 v66, v66
	v_mov_b32_e32 v67, v63
	s_nop 1
	v_permlane32_swap_b32_e32 v67, v67
	v_mul_f32_e32 v149, v149, v159
	v_cvt_f32_f16_e32 v103, v180
	v_cvt_f32_f16_e32 v44, v178
	v_cvt_f32_f16_e32 v92, v100
	s_waitcnt lgkmcnt(0)
	v_pk_add_f32 v[60:61], v[62:63], v[66:67]
	v_cvt_f32_f16_e32 v98, v181
	v_pk_fma_f32 v[60:61], v[60:61], s[6:7], v[2:3] op_sel_hi:[1,0,1]
	v_cvt_f32_f16_e32 v93, v183
	v_mul_f32_e32 v62, 0x4b800000, v61
	v_cmp_gt_f32_e32 vcc, s19, v61
	v_cvt_f32_f16_e32 v99, v88
	v_cvt_f32_f16_e32 v101, v89
	v_cndmask_b32_e32 v61, v61, v62, vcc
	v_rsq_f32_e32 v61, v61
	v_fma_mixlo_f16 v62, v149, v147, 0
	global_store_short v[56:57], v62, off offset:512
	ds_read2st64_b32 v[62:63], v4 offset0:40 offset1:44
	v_mul_f32_e32 v66, 0x45800000, v61
	v_cndmask_b32_e32 v61, v61, v66, vcc
	v_mul_f32_e32 v61, v65, v61
	v_fma_f32 v61, v71, v61, v72
	v_fmac_f32_e32 v61, v68, v69
	s_waitcnt lgkmcnt(0)
	v_fma_mixlo_f16 v61, v62, v61, 0
	v_add_f32_dpp v62, v158, v158 row_ror:8 row_mask:0xf bank_mask:0xf bound_ctrl:1
	global_store_short v[56:57], v61, off offset:1024
	v_mul_f32_e32 v61, 0x4b800000, v60
	v_add_f32_dpp v62, v62, v62 row_ror:4 row_mask:0xf bank_mask:0xf bound_ctrl:1
	v_cmp_gt_f32_e32 vcc, s19, v60
	v_mul_f32_e32 v68, 0xbfb8aa3b, v148
	v_add_f32_dpp v62, v62, v62 row_ror:2 row_mask:0xf bank_mask:0xf bound_ctrl:1
	v_cndmask_b32_e32 v60, v60, v61, vcc
	v_mul_f32_e32 v61, 0xbfb8aa3b, v156
	v_add_f32_dpp v62, v62, v62 row_ror:1 row_mask:0xf bank_mask:0xf bound_ctrl:1
	v_exp_f32_e32 v61, v61
	v_mov_b32_e32 v65, v62
	s_nop 1
	v_permlane16_swap_b32_e32 v65, v65
	v_rsq_f32_e32 v60, v60
	v_exp_f32_e32 v68, v68
	v_add_f32_e32 v61, 1.0, v61
	v_rcp_f32_e32 v61, v61
	s_waitcnt lgkmcnt(0)
	v_add_f32_e32 v62, v62, v65
	v_mov_b32_e32 v65, v62
	s_nop 1
	v_permlane32_swap_b32_e32 v65, v65
	v_mul_f32_e32 v66, 0x45800000, v60
	v_cndmask_b32_e32 v60, v60, v66, vcc
	v_mul_f32_e32 v60, v60, v64
	v_mul_f32_e32 v61, v61, v156
	v_fma_mixlo_f16 v60, v61, v60, 0
	global_store_short v[56:57], v60, off offset:1536
	s_waitcnt lgkmcnt(0)
	v_add_f32_e32 v56, v62, v65
	v_sub_f32_e32 v57, v154, v139
	v_add_f32_e32 v60, -1.0, v157
	v_fma_mix_f32 v59, v56, s18, v59 op_sel_hi:[0,0,1]
	v_sub_f32_e32 v56, v155, v140
	v_fma_mix_f32 v57, v76, v57, v144 op_sel_hi:[0,0,1]
	v_fma_f32 v60, v74, v60, 1.0
	v_fma_mix_f32 v56, v75, v56, v143 op_sel_hi:[0,0,1]
	v_mul_f32_e32 v57, v57, v60
	v_mul_f32_e32 v60, v56, v57
	v_mul_f32_e32 v56, v73, v60
	v_mov_b32_e32 v61, 0
	v_cvt_f32_f16_e32 v57, v136
	v_mov_b32_e32 v65, 0
	v_mov_b32_dpp v61, v56 row_ror:8 row_mask:0xf bank_mask:0xf
	v_cvt_f32_f16_e32 v56, v137
	v_fmac_f32_e32 v61, v73, v60
	v_mov_b32_e32 v64, 0
	v_add_f32_e32 v68, 1.0, v68
	v_add_f32_dpp v60, v61, v61 row_ror:4 row_mask:0xf bank_mask:0xf bound_ctrl:1
	v_rcp_f32_e32 v68, v68
	v_sub_f32_e32 v62, v153, v138
	v_add_f32_dpp v66, v60, v60 row_ror:2 row_mask:0xf bank_mask:0xf bound_ctrl:1
	v_pk_mul_f32 v[60:61], v[56:57], v[56:57]
	v_fma_mix_f32 v62, v77, v62, v135 op_sel_hi:[0,0,1]
	v_add_f32_dpp v66, v66, v66 row_ror:1 row_mask:0xf bank_mask:0xf bound_ctrl:1
	v_mov_b32_dpp v65, v61 row_ror:8 row_mask:0xf bank_mask:0xf
	v_mov_b32_dpp v64, v60 row_ror:8 row_mask:0xf bank_mask:0xf
	v_pk_fma_f32 v[60:61], v[56:57], v[56:57], v[64:65]
	v_mov_b32_e32 v65, 0
	v_mov_b32_e32 v64, 0
	v_mov_b32_e32 v67, v66
	s_nop 1
	v_permlane16_swap_b32_e32 v67, v67
	v_mov_b32_dpp v65, v61 row_ror:4 row_mask:0xf bank_mask:0xf
	v_mov_b32_dpp v64, v60 row_ror:4 row_mask:0xf bank_mask:0xf
	v_pk_add_f32 v[60:61], v[60:61], v[64:65]
	v_mov_b32_e32 v65, 0
	v_mov_b32_e32 v64, 0
	s_waitcnt lgkmcnt(0)
	v_add_f32_e32 v66, v66, v67
	v_mov_b32_dpp v65, v61 row_ror:2 row_mask:0xf bank_mask:0xf
	v_mov_b32_dpp v64, v60 row_ror:2 row_mask:0xf bank_mask:0xf
	v_pk_add_f32 v[60:61], v[60:61], v[64:65]
	v_mov_b32_e32 v65, 0
	v_mov_b32_e32 v64, 0
	v_mov_b32_e32 v67, v66
	s_nop 1
	v_permlane32_swap_b32_e32 v67, v67
	v_mov_b32_dpp v65, v61 row_ror:1 row_mask:0xf bank_mask:0xf
	v_mov_b32_dpp v64, v60 row_ror:1 row_mask:0xf bank_mask:0xf
	v_pk_add_f32 v[60:61], v[60:61], v[64:65]
	v_mov_b32_e32 v65, v61
	s_nop 1
	v_permlane16_swap_b32_e32 v65, v65
	v_mov_b32_e32 v64, v60
	s_nop 1
	v_permlane16_swap_b32_e32 v64, v64
	s_waitcnt lgkmcnt(2)
	v_add_f32_e32 v66, v66, v67
	s_waitcnt vmcnt(6)
	v_cvt_f32_f16_e32 v102, v9
	v_cvt_f32_f16_e32 v90, v90
	v_cvt_f32_f16_e32 v87, v184
	s_waitcnt lgkmcnt(0)
	v_pk_add_f32 v[60:61], v[60:61], v[64:65]
	v_mov_b32_e32 v65, v61
	s_nop 1
	v_permlane32_swap_b32_e32 v65, v65
	v_mov_b32_e32 v64, v60
	s_nop 1
	v_permlane32_swap_b32_e32 v64, v64
	v_cvt_f32_f16_e32 v97, v14
	s_mov_b32 s24, 8
	s_mov_b64 s[12:13], 0
	s_waitcnt lgkmcnt(0)
	v_pk_add_f32 v[60:61], v[60:61], v[64:65]
	s_nop 0
	v_pk_fma_f32 v[60:61], v[60:61], s[6:7], v[0:1] op_sel_hi:[1,0,0]
	s_nop 0
	v_mul_f32_e32 v64, 0x4b800000, v61
	v_cmp_gt_f32_e32 vcc, s19, v61
	s_nop 1
	v_cndmask_b32_e32 v61, v61, v64, vcc
	v_rsq_f32_e32 v61, v61
	v_mul_f32_e32 v64, v68, v148
	v_mul_f32_e32 v65, 0x45800000, v61
	v_cndmask_b32_e32 v61, v61, v65, vcc
	v_mul_f32_e32 v57, v61, v57
	v_mul_f32_e32 v57, v13, v57
	v_fma_mixlo_f16 v57, v64, v57, 0
	global_store_short v[52:53], v57, off
	v_mul_f32_e32 v57, 0x4b800000, v60
	v_cmp_gt_f32_e32 vcc, s19, v60
	v_mov_b32_e32 v64, 0
	v_mov_b32_e32 v65, 0
	v_cndmask_b32_e32 v57, v60, v57, vcc
	v_pk_mul_f32 v[60:61], v[58:59], v[58:59]
	v_rsq_f32_e32 v57, v57
	s_nop 0
	v_mov_b32_dpp v64, v60 row_ror:8 row_mask:0xf bank_mask:0xf
	v_mov_b32_dpp v65, v61 row_ror:8 row_mask:0xf bank_mask:0xf
	v_pk_fma_f32 v[60:61], v[58:59], v[58:59], v[64:65]
	v_mov_b32_e32 v64, 0
	v_mov_b32_e32 v65, 0
	v_mul_f32_e32 v67, 0x45800000, v57
	v_mov_b32_dpp v64, v60 row_ror:4 row_mask:0xf bank_mask:0xf
	v_mov_b32_dpp v65, v61 row_ror:4 row_mask:0xf bank_mask:0xf
	v_pk_add_f32 v[60:61], v[60:61], v[64:65]
	v_mov_b32_e32 v64, 0
	v_mov_b32_e32 v65, 0
	v_cndmask_b32_e32 v57, v57, v67, vcc
	v_mov_b32_dpp v64, v60 row_ror:2 row_mask:0xf bank_mask:0xf
	v_mov_b32_dpp v65, v61 row_ror:2 row_mask:0xf bank_mask:0xf
	v_pk_add_f32 v[60:61], v[60:61], v[64:65]
	v_mov_b32_e32 v64, 0
	v_mov_b32_e32 v65, 0
	v_mul_f32_e32 v67, 0xbfb8aa3b, v146
	v_mov_b32_dpp v64, v60 row_ror:1 row_mask:0xf bank_mask:0xf
	v_mov_b32_dpp v65, v61 row_ror:1 row_mask:0xf bank_mask:0xf
	v_pk_add_f32 v[60:61], v[60:61], v[64:65]
	v_mov_b32_e32 v64, v60
	s_nop 1
	v_permlane16_swap_b32_e32 v64, v64
	v_mov_b32_e32 v65, v61
	s_nop 1
	v_permlane16_swap_b32_e32 v65, v65
	v_exp_f32_e32 v67, v67
	v_mul_f32_e32 v56, v57, v56
	v_mul_f32_e32 v68, v70, v56
	s_waitcnt lgkmcnt(0)
	v_pk_add_f32 v[60:61], v[60:61], v[64:65]
	v_mov_b32_e32 v64, v60
	s_nop 1
	v_permlane32_swap_b32_e32 v64, v64
	v_mov_b32_e32 v65, v61
	s_nop 1
	v_permlane32_swap_b32_e32 v65, v65
	v_add_f32_e32 v56, 1.0, v67
	v_rcp_f32_e32 v67, v56
	s_waitcnt lgkmcnt(0)
	v_pk_add_f32 v[56:57], v[60:61], v[64:65]
	s_nop 0
	v_pk_fma_f32 v[56:57], v[56:57], s[6:7], v[2:3] op_sel_hi:[1,0,1]
	s_nop 0
	v_mul_f32_e32 v60, 0x4b800000, v57
	v_cmp_gt_f32_e32 vcc, s19, v57
	s_nop 1
	v_cndmask_b32_e32 v57, v57, v60, vcc
	v_rsq_f32_e32 v57, v57
	v_mul_f32_e32 v60, v67, v146
	v_fma_mixlo_f16 v60, v60, v68, 0
	global_store_short v[52:53], v60, off offset:512
	v_mul_f32_e32 v60, 0x45800000, v57
	v_cndmask_b32_e32 v57, v57, v60, vcc
	v_mul_f32_e32 v57, v59, v57
	v_fma_f32 v57, v71, v57, v72
	v_fmac_f32_e32 v57, v62, v66
	v_add_f32_dpp v59, v145, v145 row_ror:8 row_mask:0xf bank_mask:0xf bound_ctrl:1
	v_fma_mixlo_f16 v57, v63, v57, 0
	global_store_short v[52:53], v57, off offset:1024
	v_add_f32_dpp v59, v59, v59 row_ror:4 row_mask:0xf bank_mask:0xf bound_ctrl:1
	v_mul_f32_e32 v57, 0x4b800000, v56
	v_cmp_gt_f32_e32 vcc, s19, v56
	v_add_f32_dpp v59, v59, v59 row_ror:2 row_mask:0xf bank_mask:0xf bound_ctrl:1
	v_mul_f32_e32 v63, 0xbfb8aa3b, v134
	v_cndmask_b32_e32 v56, v56, v57, vcc
	v_mul_f32_e32 v57, 0xbfb8aa3b, v141
	v_add_f32_dpp v59, v59, v59 row_ror:1 row_mask:0xf bank_mask:0xf bound_ctrl:1
	v_exp_f32_e32 v57, v57
	v_mov_b32_e32 v60, v59
	s_nop 1
	v_permlane16_swap_b32_e32 v60, v60
	v_rsq_f32_e32 v56, v56
	v_exp_f32_e32 v63, v63
	v_add_f32_e32 v57, 1.0, v57
	v_rcp_f32_e32 v57, v57
	s_waitcnt lgkmcnt(0)
	v_add_f32_e32 v59, v59, v60
	v_mov_b32_e32 v60, v59
	s_nop 1
	v_permlane32_swap_b32_e32 v60, v60
	v_mul_f32_e32 v61, 0x45800000, v56
	v_cndmask_b32_e32 v56, v56, v61, vcc
	v_mul_f32_e32 v56, v56, v58
	v_mul_f32_e32 v57, v57, v141
	v_fma_mixlo_f16 v56, v57, v56, 0
	global_store_short v[52:53], v56, off offset:1536
	s_waitcnt lgkmcnt(0)
	v_add_f32_e32 v52, v59, v60
	v_sub_f32_e32 v53, v139, v126
	v_add_f32_e32 v56, -1.0, v142
	v_fma_mix_f32 v55, v52, s18, v55 op_sel_hi:[0,0,1]
	v_sub_f32_e32 v52, v140, v127
	v_fma_mix_f32 v53, v76, v53, v132 op_sel_hi:[0,0,1]
	v_fma_f32 v56, v74, v56, 1.0
	v_fma_mix_f32 v52, v75, v52, v131 op_sel_hi:[0,0,1]
	v_mul_f32_e32 v53, v53, v56
	v_mul_f32_e32 v56, v52, v53
	v_mul_f32_e32 v52, v73, v56
	v_mov_b32_e32 v57, 0
	v_cvt_f32_f16_e32 v53, v123
	v_mov_b32_e32 v59, 0
	v_mov_b32_dpp v57, v52 row_ror:8 row_mask:0xf bank_mask:0xf
	v_cvt_f32_f16_e32 v52, v124
	v_fmac_f32_e32 v57, v73, v56
	v_mov_b32_e32 v58, 0
	v_add_f32_e32 v63, 1.0, v63
	v_add_f32_dpp v56, v57, v57 row_ror:4 row_mask:0xf bank_mask:0xf bound_ctrl:1
	v_rcp_f32_e32 v63, v63
	v_sub_f32_e32 v60, v138, v125
	v_add_f32_dpp v61, v56, v56 row_ror:2 row_mask:0xf bank_mask:0xf bound_ctrl:1
	v_pk_mul_f32 v[56:57], v[52:53], v[52:53]
	v_fma_mix_f32 v60, v77, v60, v122 op_sel_hi:[0,0,1]
	v_add_f32_dpp v61, v61, v61 row_ror:1 row_mask:0xf bank_mask:0xf bound_ctrl:1
	v_mov_b32_dpp v59, v57 row_ror:8 row_mask:0xf bank_mask:0xf
	v_mov_b32_dpp v58, v56 row_ror:8 row_mask:0xf bank_mask:0xf
	v_pk_fma_f32 v[56:57], v[52:53], v[52:53], v[58:59]
	v_mov_b32_e32 v59, 0
	v_mov_b32_e32 v58, 0
	v_mov_b32_e32 v62, v61
	s_nop 1
	v_permlane16_swap_b32_e32 v62, v62
	v_mov_b32_dpp v59, v57 row_ror:4 row_mask:0xf bank_mask:0xf
	v_mov_b32_dpp v58, v56 row_ror:4 row_mask:0xf bank_mask:0xf
	v_pk_add_f32 v[56:57], v[56:57], v[58:59]
	v_mov_b32_e32 v59, 0
	v_mov_b32_e32 v58, 0
	s_waitcnt lgkmcnt(0)
	v_add_f32_e32 v61, v61, v62
	v_mov_b32_dpp v59, v57 row_ror:2 row_mask:0xf bank_mask:0xf
	v_mov_b32_dpp v58, v56 row_ror:2 row_mask:0xf bank_mask:0xf
	v_pk_add_f32 v[56:57], v[56:57], v[58:59]
	v_mov_b32_e32 v59, 0
	v_mov_b32_e32 v58, 0
	v_mov_b32_e32 v62, v61
	s_nop 1
	v_permlane32_swap_b32_e32 v62, v62
	v_mov_b32_dpp v59, v57 row_ror:1 row_mask:0xf bank_mask:0xf
	v_mov_b32_dpp v58, v56 row_ror:1 row_mask:0xf bank_mask:0xf
	v_pk_add_f32 v[56:57], v[56:57], v[58:59]
	v_mov_b32_e32 v59, v57
	s_nop 1
	v_permlane16_swap_b32_e32 v59, v59
	v_mov_b32_e32 v58, v56
	s_nop 1
	v_permlane16_swap_b32_e32 v58, v58
	s_waitcnt lgkmcnt(2)
	v_add_f32_e32 v61, v61, v62
	s_waitcnt lgkmcnt(0)
	v_pk_add_f32 v[56:57], v[56:57], v[58:59]
	v_mov_b32_e32 v59, v57
	s_nop 1
	v_permlane32_swap_b32_e32 v59, v59
	v_mov_b32_e32 v58, v56
	s_nop 1
	v_permlane32_swap_b32_e32 v58, v58
	s_waitcnt lgkmcnt(0)
	v_pk_add_f32 v[56:57], v[56:57], v[58:59]
	s_nop 0
	v_pk_fma_f32 v[56:57], v[56:57], s[6:7], v[0:1] op_sel_hi:[1,0,0]
	s_nop 0
	v_mul_f32_e32 v58, 0x4b800000, v57
	v_cmp_gt_f32_e32 vcc, s19, v57
	s_nop 1
	v_cndmask_b32_e32 v57, v57, v58, vcc
	v_rsq_f32_e32 v57, v57
	v_mul_f32_e32 v58, v63, v134
	v_mul_f32_e32 v59, 0x45800000, v57
	v_cndmask_b32_e32 v57, v57, v59, vcc
	v_mul_f32_e32 v53, v57, v53
	v_mul_f32_e32 v57, 0x4b800000, v56
	v_cmp_gt_f32_e32 vcc, s19, v56
	v_mul_f32_e32 v53, v13, v53
	v_fma_mixlo_f16 v53, v58, v53, 0
	v_cndmask_b32_e32 v56, v56, v57, vcc
	v_rsq_f32_e32 v62, v56
	v_mul_f32_e32 v56, 0xbfb8aa3b, v133
	v_exp_f32_e32 v63, v56
	v_pk_mul_f32 v[56:57], v[54:55], v[54:55]
	v_mov_b32_e32 v58, 0
	v_mov_b32_e32 v59, 0
	global_store_short v[50:51], v53, off
	v_mov_b32_dpp v58, v56 row_ror:8 row_mask:0xf bank_mask:0xf
	v_mov_b32_dpp v59, v57 row_ror:8 row_mask:0xf bank_mask:0xf
	v_pk_fma_f32 v[56:57], v[54:55], v[54:55], v[58:59]
	v_mov_b32_e32 v58, 0
	v_mov_b32_e32 v59, 0
	v_mul_f32_e32 v53, 0x45800000, v62
	v_mov_b32_dpp v58, v56 row_ror:4 row_mask:0xf bank_mask:0xf
	v_mov_b32_dpp v59, v57 row_ror:4 row_mask:0xf bank_mask:0xf
	v_pk_add_f32 v[56:57], v[56:57], v[58:59]
	v_mov_b32_e32 v58, 0
	v_mov_b32_e32 v59, 0
	v_cndmask_b32_e32 v53, v62, v53, vcc
	v_mov_b32_dpp v58, v56 row_ror:2 row_mask:0xf bank_mask:0xf
	v_mov_b32_dpp v59, v57 row_ror:2 row_mask:0xf bank_mask:0xf
	v_pk_add_f32 v[56:57], v[56:57], v[58:59]
	v_mov_b32_e32 v58, 0
	v_mov_b32_e32 v59, 0
	v_mul_f32_e32 v52, v53, v52
	v_mov_b32_dpp v58, v56 row_ror:1 row_mask:0xf bank_mask:0xf
	v_mov_b32_dpp v59, v57 row_ror:1 row_mask:0xf bank_mask:0xf
	v_pk_add_f32 v[56:57], v[56:57], v[58:59]
	v_mov_b32_e32 v58, v56
	s_nop 1
	v_permlane16_swap_b32_e32 v58, v58
	v_mov_b32_e32 v59, v57
	s_nop 1
	v_permlane16_swap_b32_e32 v59, v59
	v_mul_f32_e32 v62, v70, v52
	v_add_f32_e32 v63, 1.0, v63
	v_rcp_f32_e32 v63, v63
	s_waitcnt lgkmcnt(0)
	v_pk_add_f32 v[56:57], v[56:57], v[58:59]
	v_mov_b32_e32 v58, v56
	s_nop 1
	v_permlane32_swap_b32_e32 v58, v58
	v_mov_b32_e32 v59, v57
	s_nop 1
	v_permlane32_swap_b32_e32 v59, v59
	v_mul_f32_e32 v63, v63, v133
	s_waitcnt lgkmcnt(0)
	v_pk_add_f32 v[52:53], v[56:57], v[58:59]
	s_nop 0
	v_pk_fma_f32 v[52:53], v[52:53], s[6:7], v[2:3] op_sel_hi:[1,0,1]
	s_nop 0
	v_mul_f32_e32 v56, 0x4b800000, v53
	v_cmp_gt_f32_e32 vcc, s19, v53
	s_nop 1
	v_cndmask_b32_e32 v53, v53, v56, vcc
	v_rsq_f32_e32 v53, v53
	v_fma_mixlo_f16 v56, v63, v62, 0
	global_store_short v[50:51], v56, off offset:512
	ds_read2st64_b32 v[56:57], v4 offset0:48 offset1:52
	v_mul_f32_e32 v58, 0x45800000, v53
	v_cndmask_b32_e32 v53, v53, v58, vcc
	v_mul_f32_e32 v53, v55, v53
	v_fma_f32 v53, v71, v53, v72
	v_fmac_f32_e32 v53, v60, v61
	v_add_f32_dpp v55, v130, v130 row_ror:8 row_mask:0xf bank_mask:0xf bound_ctrl:1
	s_waitcnt lgkmcnt(0)
	v_fma_mixlo_f16 v53, v56, v53, 0
	global_store_short v[50:51], v53, off offset:1024
	v_add_f32_dpp v55, v55, v55 row_ror:4 row_mask:0xf bank_mask:0xf bound_ctrl:1
	v_mul_f32_e32 v53, 0x4b800000, v52
	v_cmp_gt_f32_e32 vcc, s19, v52
	v_add_f32_dpp v55, v55, v55 row_ror:2 row_mask:0xf bank_mask:0xf bound_ctrl:1
	v_mul_f32_e32 v60, 0xbfb8aa3b, v119
	v_cndmask_b32_e32 v52, v52, v53, vcc
	v_mul_f32_e32 v53, 0xbfb8aa3b, v128
	v_add_f32_dpp v55, v55, v55 row_ror:1 row_mask:0xf bank_mask:0xf bound_ctrl:1
	v_exp_f32_e32 v53, v53
	v_mov_b32_e32 v56, v55
	s_nop 1
	v_permlane16_swap_b32_e32 v56, v56
	v_rsq_f32_e32 v52, v52
	v_exp_f32_e32 v60, v60
	v_add_f32_e32 v53, 1.0, v53
	v_rcp_f32_e32 v53, v53
	s_waitcnt lgkmcnt(0)
	v_add_f32_e32 v55, v55, v56
	v_mov_b32_e32 v56, v55
	s_nop 1
	v_permlane32_swap_b32_e32 v56, v56
	v_mul_f32_e32 v58, 0x45800000, v52
	v_cndmask_b32_e32 v52, v52, v58, vcc
	v_mul_f32_e32 v52, v52, v54
	v_mul_f32_e32 v53, v53, v128
	v_fma_mixlo_f16 v52, v53, v52, 0
	global_store_short v[50:51], v52, off offset:1536
	s_waitcnt lgkmcnt(0)
	v_add_f32_e32 v50, v55, v56
	v_sub_f32_e32 v51, v126, v111
	v_add_f32_e32 v52, -1.0, v129
	v_fma_mix_f32 v49, v50, s18, v49 op_sel_hi:[0,0,1]
	v_sub_f32_e32 v50, v127, v112
	v_fma_mix_f32 v51, v76, v51, v118 op_sel_hi:[0,0,1]
	v_fma_f32 v52, v74, v52, 1.0
	v_fma_mix_f32 v50, v75, v50, v117 op_sel_hi:[0,0,1]
	v_mul_f32_e32 v51, v51, v52
	v_mul_f32_e32 v52, v50, v51
	v_mul_f32_e32 v50, v73, v52
	v_mov_b32_e32 v53, 0
	v_cvt_f32_f16_e32 v51, v120
	v_mov_b32_e32 v55, 0
	v_mov_b32_dpp v53, v50 row_ror:8 row_mask:0xf bank_mask:0xf
	v_cvt_f32_f16_e32 v50, v121
	v_fmac_f32_e32 v53, v73, v52
	v_mov_b32_e32 v54, 0
	v_add_f32_e32 v60, 1.0, v60
	v_add_f32_dpp v52, v53, v53 row_ror:4 row_mask:0xf bank_mask:0xf bound_ctrl:1
	v_rcp_f32_e32 v60, v60
	v_sub_f32_e32 v56, v125, v110
	v_add_f32_dpp v58, v52, v52 row_ror:2 row_mask:0xf bank_mask:0xf bound_ctrl:1
	v_pk_mul_f32 v[52:53], v[50:51], v[50:51]
	v_fma_mix_f32 v56, v77, v56, v109 op_sel_hi:[0,0,1]
	v_add_f32_dpp v58, v58, v58 row_ror:1 row_mask:0xf bank_mask:0xf bound_ctrl:1
	v_mov_b32_dpp v55, v53 row_ror:8 row_mask:0xf bank_mask:0xf
	v_mov_b32_dpp v54, v52 row_ror:8 row_mask:0xf bank_mask:0xf
	v_pk_fma_f32 v[52:53], v[50:51], v[50:51], v[54:55]
	v_mov_b32_e32 v55, 0
	v_mov_b32_e32 v54, 0
	v_mov_b32_e32 v59, v58
	s_nop 1
	v_permlane16_swap_b32_e32 v59, v59
	v_mov_b32_dpp v55, v53 row_ror:4 row_mask:0xf bank_mask:0xf
	v_mov_b32_dpp v54, v52 row_ror:4 row_mask:0xf bank_mask:0xf
	v_pk_add_f32 v[52:53], v[52:53], v[54:55]
	v_mov_b32_e32 v55, 0
	v_mov_b32_e32 v54, 0
	s_waitcnt lgkmcnt(0)
	v_add_f32_e32 v58, v58, v59
	v_mov_b32_dpp v55, v53 row_ror:2 row_mask:0xf bank_mask:0xf
	v_mov_b32_dpp v54, v52 row_ror:2 row_mask:0xf bank_mask:0xf
	v_pk_add_f32 v[52:53], v[52:53], v[54:55]
	v_mov_b32_e32 v55, 0
	v_mov_b32_e32 v54, 0
	v_mov_b32_e32 v59, v58
	s_nop 1
	v_permlane32_swap_b32_e32 v59, v59
	v_mov_b32_dpp v55, v53 row_ror:1 row_mask:0xf bank_mask:0xf
	v_mov_b32_dpp v54, v52 row_ror:1 row_mask:0xf bank_mask:0xf
	v_pk_add_f32 v[52:53], v[52:53], v[54:55]
	v_mov_b32_e32 v55, v53
	s_nop 1
	v_permlane16_swap_b32_e32 v55, v55
	v_mov_b32_e32 v54, v52
	s_nop 1
	v_permlane16_swap_b32_e32 v54, v54
	s_waitcnt lgkmcnt(2)
	v_add_f32_e32 v58, v58, v59
	s_waitcnt lgkmcnt(0)
	v_pk_add_f32 v[52:53], v[52:53], v[54:55]
	v_mov_b32_e32 v55, v53
	s_nop 1
	v_permlane32_swap_b32_e32 v55, v55
	v_mov_b32_e32 v54, v52
	s_nop 1
	v_permlane32_swap_b32_e32 v54, v54
	s_waitcnt lgkmcnt(0)
	v_pk_add_f32 v[52:53], v[52:53], v[54:55]
	s_nop 0
	v_pk_fma_f32 v[52:53], v[52:53], s[6:7], v[0:1] op_sel_hi:[1,0,0]
	s_nop 0
	v_mul_f32_e32 v54, 0x4b800000, v53
	v_cmp_gt_f32_e32 vcc, s19, v53
	s_nop 1
	v_cndmask_b32_e32 v53, v53, v54, vcc
	v_rsq_f32_e32 v53, v53
	v_mul_f32_e32 v54, v60, v119
	v_mul_f32_e32 v55, 0x45800000, v53
	v_cndmask_b32_e32 v53, v53, v55, vcc
	v_mul_f32_e32 v51, v53, v51
	v_mul_f32_e32 v51, v13, v51
	v_fma_mixlo_f16 v51, v54, v51, 0
	global_store_short v[46:47], v51, off
	v_mul_f32_e32 v51, 0x4b800000, v52
	v_cmp_gt_f32_e32 vcc, s19, v52
	v_mov_b32_e32 v54, 0
	v_mov_b32_e32 v55, 0
	v_cndmask_b32_e32 v51, v52, v51, vcc
	v_pk_mul_f32 v[52:53], v[48:49], v[48:49]
	v_rsq_f32_e32 v51, v51
	s_nop 0
	v_mov_b32_dpp v54, v52 row_ror:8 row_mask:0xf bank_mask:0xf
	v_mov_b32_dpp v55, v53 row_ror:8 row_mask:0xf bank_mask:0xf
	v_pk_fma_f32 v[52:53], v[48:49], v[48:49], v[54:55]
	v_mov_b32_e32 v54, 0
	v_mov_b32_e32 v55, 0
	v_mul_f32_e32 v59, 0x45800000, v51
	v_mov_b32_dpp v54, v52 row_ror:4 row_mask:0xf bank_mask:0xf
	v_mov_b32_dpp v55, v53 row_ror:4 row_mask:0xf bank_mask:0xf
	v_pk_add_f32 v[52:53], v[52:53], v[54:55]
	v_mov_b32_e32 v54, 0
	v_mov_b32_e32 v55, 0
	v_cndmask_b32_e32 v51, v51, v59, vcc
	v_mov_b32_dpp v54, v52 row_ror:2 row_mask:0xf bank_mask:0xf
	v_mov_b32_dpp v55, v53 row_ror:2 row_mask:0xf bank_mask:0xf
	v_pk_add_f32 v[52:53], v[52:53], v[54:55]
	v_mov_b32_e32 v54, 0
	v_mov_b32_e32 v55, 0
	v_mul_f32_e32 v59, 0xbfb8aa3b, v116
	v_mov_b32_dpp v54, v52 row_ror:1 row_mask:0xf bank_mask:0xf
	v_mov_b32_dpp v55, v53 row_ror:1 row_mask:0xf bank_mask:0xf
	v_pk_add_f32 v[52:53], v[52:53], v[54:55]
	v_mov_b32_e32 v54, v52
	s_nop 1
	v_permlane16_swap_b32_e32 v54, v54
	v_mov_b32_e32 v55, v53
	s_nop 1
	v_permlane16_swap_b32_e32 v55, v55
	v_exp_f32_e32 v59, v59
	v_mul_f32_e32 v50, v51, v50
	v_mul_f32_e32 v60, v70, v50
	s_waitcnt lgkmcnt(0)
	v_pk_add_f32 v[52:53], v[52:53], v[54:55]
	v_mov_b32_e32 v54, v52
	s_nop 1
	v_permlane32_swap_b32_e32 v54, v54
	v_mov_b32_e32 v55, v53
	s_nop 1
	v_permlane32_swap_b32_e32 v55, v55
	v_add_f32_e32 v50, 1.0, v59
	v_rcp_f32_e32 v59, v50
	s_waitcnt lgkmcnt(0)
	v_pk_add_f32 v[50:51], v[52:53], v[54:55]
	s_nop 0
	v_pk_fma_f32 v[50:51], v[50:51], s[6:7], v[2:3] op_sel_hi:[1,0,1]
	v_mul_f32_e32 v55, 0xbfb8aa3b, v108
	v_mul_f32_e32 v52, 0x4b800000, v51
	v_cmp_gt_f32_e32 vcc, s19, v51
	v_exp_f32_e32 v55, v55
	s_nop 0
	v_cndmask_b32_e32 v51, v51, v52, vcc
	v_rsq_f32_e32 v51, v51
	v_mul_f32_e32 v52, v59, v116
	v_fma_mixlo_f16 v52, v52, v60, 0
	global_store_short v[46:47], v52, off offset:512
	v_mul_f32_e32 v52, 0x45800000, v51
	v_cndmask_b32_e32 v51, v51, v52, vcc
	v_mul_f32_e32 v49, v49, v51
	v_fma_f32 v49, v71, v49, v72
	v_fmac_f32_e32 v49, v56, v58
	v_add_f32_dpp v51, v115, v115 row_ror:8 row_mask:0xf bank_mask:0xf bound_ctrl:1
	v_fma_mixlo_f16 v49, v57, v49, 0
	global_store_short v[46:47], v49, off offset:1024
	v_add_f32_dpp v51, v51, v51 row_ror:4 row_mask:0xf bank_mask:0xf bound_ctrl:1
	v_mul_f32_e32 v49, 0x4b800000, v50
	v_cmp_gt_f32_e32 vcc, s19, v50
	v_add_f32_dpp v51, v51, v51 row_ror:2 row_mask:0xf bank_mask:0xf bound_ctrl:1
	v_add_f32_e32 v55, 1.0, v55
	v_cndmask_b32_e32 v49, v50, v49, vcc
	v_mul_f32_e32 v50, 0xbfb8aa3b, v113
	v_add_f32_dpp v51, v51, v51 row_ror:1 row_mask:0xf bank_mask:0xf bound_ctrl:1
	v_exp_f32_e32 v50, v50
	v_mov_b32_e32 v52, v51
	s_nop 1
	v_permlane16_swap_b32_e32 v52, v52
	v_rsq_f32_e32 v49, v49
	v_rcp_f32_e32 v55, v55
	v_add_f32_e32 v50, 1.0, v50
	v_rcp_f32_e32 v50, v50
	s_waitcnt lgkmcnt(0)
	v_add_f32_e32 v51, v51, v52
	v_mov_b32_e32 v52, v51
	s_nop 1
	v_permlane32_swap_b32_e32 v52, v52
	v_mul_f32_e32 v53, 0x45800000, v49
	v_cndmask_b32_e32 v49, v49, v53, vcc
	v_mul_f32_e32 v48, v49, v48
	v_mul_f32_e32 v49, v50, v113
	v_fma_mixlo_f16 v48, v49, v48, 0
	global_store_short v[46:47], v48, off offset:1536
	s_waitcnt lgkmcnt(0)
	v_add_f32_e32 v46, v51, v52
	v_sub_f32_e32 v47, v111, v94
	v_add_f32_e32 v48, -1.0, v114
	v_fma_mix_f32 v45, v46, s18, v45 op_sel_hi:[0,0,1]
	v_sub_f32_e32 v46, v112, v95
	v_fma_mix_f32 v47, v76, v47, v105 op_sel_hi:[0,0,1]
	v_fma_f32 v48, v74, v48, 1.0
	v_fma_mix_f32 v46, v75, v46, v104 op_sel_hi:[0,0,1]
	v_mul_f32_e32 v47, v47, v48
	v_mul_f32_e32 v48, v46, v47
	v_mul_f32_e32 v46, v73, v48
	v_mov_b32_e32 v49, 0
	v_cvt_f32_f16_e32 v47, v106
	v_mov_b32_e32 v51, 0
	v_mov_b32_dpp v49, v46 row_ror:8 row_mask:0xf bank_mask:0xf
	v_cvt_f32_f16_e32 v46, v107
	v_fmac_f32_e32 v49, v73, v48
	v_mov_b32_e32 v50, 0
	v_sub_f32_e32 v52, v110, v92
	v_add_f32_dpp v48, v49, v49 row_ror:4 row_mask:0xf bank_mask:0xf bound_ctrl:1
	v_fma_mix_f32 v52, v77, v52, v100 op_sel_hi:[0,0,1]
	s_nop 0
	v_add_f32_dpp v53, v48, v48 row_ror:2 row_mask:0xf bank_mask:0xf bound_ctrl:1
	v_pk_mul_f32 v[48:49], v[46:47], v[46:47]
	s_nop 0
	v_add_f32_dpp v53, v53, v53 row_ror:1 row_mask:0xf bank_mask:0xf bound_ctrl:1
	v_mov_b32_dpp v51, v49 row_ror:8 row_mask:0xf bank_mask:0xf
	v_mov_b32_dpp v50, v48 row_ror:8 row_mask:0xf bank_mask:0xf
	v_pk_fma_f32 v[48:49], v[46:47], v[46:47], v[50:51]
	v_mov_b32_e32 v51, 0
	v_mov_b32_e32 v50, 0
	v_mov_b32_e32 v54, v53
	s_nop 1
	v_permlane16_swap_b32_e32 v54, v54
	v_mov_b32_dpp v51, v49 row_ror:4 row_mask:0xf bank_mask:0xf
	v_mov_b32_dpp v50, v48 row_ror:4 row_mask:0xf bank_mask:0xf
	v_pk_add_f32 v[48:49], v[48:49], v[50:51]
	v_mov_b32_e32 v51, 0
	v_mov_b32_e32 v50, 0
	s_waitcnt lgkmcnt(0)
	v_add_f32_e32 v53, v53, v54
	v_mov_b32_dpp v51, v49 row_ror:2 row_mask:0xf bank_mask:0xf
	v_mov_b32_dpp v50, v48 row_ror:2 row_mask:0xf bank_mask:0xf
	v_pk_add_f32 v[48:49], v[48:49], v[50:51]
	v_mov_b32_e32 v51, 0
	v_mov_b32_e32 v50, 0
	v_mov_b32_e32 v54, v53
	s_nop 1
	v_permlane32_swap_b32_e32 v54, v54
	v_mov_b32_dpp v51, v49 row_ror:1 row_mask:0xf bank_mask:0xf
	v_mov_b32_dpp v50, v48 row_ror:1 row_mask:0xf bank_mask:0xf
	v_pk_add_f32 v[48:49], v[48:49], v[50:51]
	v_mov_b32_e32 v51, v49
	s_nop 1
	v_permlane16_swap_b32_e32 v51, v51
	v_mov_b32_e32 v50, v48
	s_nop 1
	v_permlane16_swap_b32_e32 v50, v50
	s_waitcnt lgkmcnt(2)
	v_add_f32_e32 v53, v53, v54
	s_waitcnt lgkmcnt(0)
	v_pk_add_f32 v[48:49], v[48:49], v[50:51]
	v_mov_b32_e32 v51, v49
	s_nop 1
	v_permlane32_swap_b32_e32 v51, v51
	v_mov_b32_e32 v50, v48
	s_nop 1
	v_permlane32_swap_b32_e32 v50, v50
	s_waitcnt lgkmcnt(0)
	v_pk_add_f32 v[48:49], v[48:49], v[50:51]
	s_nop 0
	v_pk_fma_f32 v[48:49], v[48:49], s[6:7], v[0:1] op_sel_hi:[1,0,0]
	s_nop 0
	v_mul_f32_e32 v50, 0x4b800000, v49
	v_cmp_gt_f32_e32 vcc, s19, v49
	s_nop 1
	v_cndmask_b32_e32 v49, v49, v50, vcc
	v_rsq_f32_e32 v49, v49
	v_mul_f32_e32 v50, v55, v108
	v_mul_f32_e32 v51, 0x45800000, v49
	v_cndmask_b32_e32 v49, v49, v51, vcc
	v_mul_f32_e32 v47, v49, v47
	v_mul_f32_e32 v49, 0x4b800000, v48
	v_cmp_gt_f32_e32 vcc, s19, v48
	v_mul_f32_e32 v47, v13, v47
	v_fma_mixlo_f16 v47, v50, v47, 0
	v_cndmask_b32_e32 v48, v48, v49, vcc
	v_rsq_f32_e32 v54, v48
	v_mul_f32_e32 v48, 0xbfb8aa3b, v103
	v_exp_f32_e32 v55, v48
	v_pk_mul_f32 v[48:49], v[44:45], v[44:45]
	v_mov_b32_e32 v50, 0
	v_mov_b32_e32 v51, 0
	global_store_short v[10:11], v47, off
	v_mov_b32_dpp v50, v48 row_ror:8 row_mask:0xf bank_mask:0xf
	v_mov_b32_dpp v51, v49 row_ror:8 row_mask:0xf bank_mask:0xf
	v_pk_fma_f32 v[48:49], v[44:45], v[44:45], v[50:51]
	v_mov_b32_e32 v50, 0
	v_mov_b32_e32 v51, 0
	v_mul_f32_e32 v47, 0x45800000, v54
	v_mov_b32_dpp v50, v48 row_ror:4 row_mask:0xf bank_mask:0xf
	v_mov_b32_dpp v51, v49 row_ror:4 row_mask:0xf bank_mask:0xf
	v_pk_add_f32 v[48:49], v[48:49], v[50:51]
	v_mov_b32_e32 v50, 0
	v_mov_b32_e32 v51, 0
	v_cndmask_b32_e32 v47, v54, v47, vcc
	v_mov_b32_dpp v50, v48 row_ror:2 row_mask:0xf bank_mask:0xf
	v_mov_b32_dpp v51, v49 row_ror:2 row_mask:0xf bank_mask:0xf
	v_pk_add_f32 v[48:49], v[48:49], v[50:51]
	v_mov_b32_e32 v50, 0
	v_mov_b32_e32 v51, 0
	v_mul_f32_e32 v46, v47, v46
	v_mov_b32_dpp v50, v48 row_ror:1 row_mask:0xf bank_mask:0xf
	v_mov_b32_dpp v51, v49 row_ror:1 row_mask:0xf bank_mask:0xf
	v_pk_add_f32 v[48:49], v[48:49], v[50:51]
	v_mov_b32_e32 v50, v48
	s_nop 1
	v_permlane16_swap_b32_e32 v50, v50
	v_mov_b32_e32 v51, v49
	s_nop 1
	v_permlane16_swap_b32_e32 v51, v51
	v_mul_f32_e32 v54, v70, v46
	v_add_f32_e32 v55, 1.0, v55
	v_rcp_f32_e32 v55, v55
	s_waitcnt lgkmcnt(0)
	v_pk_add_f32 v[48:49], v[48:49], v[50:51]
	v_mov_b32_e32 v50, v48
	s_nop 1
	v_permlane32_swap_b32_e32 v50, v50
	v_mov_b32_e32 v51, v49
	s_nop 1
	v_permlane32_swap_b32_e32 v51, v51
	v_mul_f32_e32 v55, v55, v103
	s_waitcnt lgkmcnt(0)
	v_pk_add_f32 v[46:47], v[48:49], v[50:51]
	s_nop 0
	v_pk_fma_f32 v[46:47], v[46:47], s[6:7], v[2:3] op_sel_hi:[1,0,1]
	v_mul_f32_e32 v51, 0xbfb8aa3b, v90
	v_mul_f32_e32 v48, 0x4b800000, v47
	v_cmp_gt_f32_e32 vcc, s19, v47
	v_exp_f32_e32 v51, v51
	s_nop 0
	v_cndmask_b32_e32 v47, v47, v48, vcc
	v_rsq_f32_e32 v47, v47
	v_fma_mixlo_f16 v48, v55, v54, 0
	global_store_short v[10:11], v48, off offset:512
	ds_read2st64_b32 v[48:49], v4 offset0:56 offset1:60
	v_mul_f32_e32 v4, 0x45800000, v47
	v_cndmask_b32_e32 v4, v47, v4, vcc
	v_mul_f32_e32 v4, v45, v4
	v_fma_f32 v4, v71, v4, v72
	v_fmac_f32_e32 v4, v52, v53
	s_waitcnt lgkmcnt(0)
	v_fma_mixlo_f16 v4, v48, v4, 0
	global_store_short v[10:11], v4, off offset:1024
	v_mul_f32_e32 v4, 0x4b800000, v46
	v_cmp_gt_f32_e32 vcc, s19, v46
	v_mul_f32_e32 v45, 0xbfb8aa3b, v98
	v_exp_f32_e32 v45, v45
	v_cndmask_b32_e32 v4, v46, v4, vcc
	v_add_f32_dpp v46, v102, v102 row_ror:8 row_mask:0xf bank_mask:0xf bound_ctrl:1
	v_rsq_f32_e32 v4, v4
	v_add_f32_e32 v45, 1.0, v45
	v_add_f32_dpp v46, v46, v46 row_ror:4 row_mask:0xf bank_mask:0xf bound_ctrl:1
	v_rcp_f32_e32 v45, v45
	v_mul_f32_e32 v48, 0x45800000, v4
	v_add_f32_dpp v46, v46, v46 row_ror:2 row_mask:0xf bank_mask:0xf bound_ctrl:1
	v_cndmask_b32_e32 v4, v4, v48, vcc
	v_mul_f32_e32 v4, v4, v44
	v_add_f32_dpp v46, v46, v46 row_ror:1 row_mask:0xf bank_mask:0xf bound_ctrl:1
	v_mov_b32_e32 v47, v46
	s_nop 1
	v_permlane16_swap_b32_e32 v47, v47
	v_mul_f32_e32 v44, v45, v98
	v_fma_mixlo_f16 v4, v44, v4, 0
	global_store_short v[10:11], v4, off offset:1536
	v_sub_f32_e32 v10, v94, v99
	s_waitcnt lgkmcnt(0)
	v_add_f32_e32 v46, v46, v47
	v_mov_b32_e32 v47, v46
	s_nop 1
	v_permlane32_swap_b32_e32 v47, v47
	v_add_f32_e32 v11, -1.0, v93
	v_fma_mix_f32 v10, v76, v10, v88 op_sel_hi:[0,0,1]
	v_fma_f32 v11, v74, v11, 1.0
	v_mul_f32_e32 v10, v11, v10
	s_waitcnt lgkmcnt(0)
	v_add_f32_e32 v4, v46, v47
	v_fma_mix_f32 v9, v4, s18, v9 op_sel_hi:[0,0,1]
	v_sub_f32_e32 v4, v95, v101
	v_fma_mix_f32 v4, v75, v4, v89 op_sel_hi:[0,0,1]
	v_mul_f32_e32 v4, v4, v10
	v_mul_f32_e32 v10, v73, v4
	v_mov_b32_e32 v44, 0
	s_waitcnt vmcnt(21)
	v_cvt_f32_f16_e32 v11, v96
	v_mov_b32_e32 v47, 0
	v_mov_b32_dpp v44, v10 row_ror:8 row_mask:0xf bank_mask:0xf
	s_waitcnt vmcnt(20)
	v_cvt_f32_f16_e32 v10, v91
	v_fmac_f32_e32 v44, v73, v4
	v_mov_b32_e32 v46, 0
	v_add_f32_e32 v51, 1.0, v51
	v_add_f32_dpp v4, v44, v44 row_ror:4 row_mask:0xf bank_mask:0xf bound_ctrl:1
	v_pk_mul_f32 v[44:45], v[10:11], v[10:11]
	v_rcp_f32_e32 v51, v51
	v_add_f32_dpp v4, v4, v4 row_ror:2 row_mask:0xf bank_mask:0xf bound_ctrl:1
	v_mov_b32_dpp v47, v45 row_ror:8 row_mask:0xf bank_mask:0xf
	v_mov_b32_dpp v46, v44 row_ror:8 row_mask:0xf bank_mask:0xf
	v_pk_fma_f32 v[44:45], v[10:11], v[10:11], v[46:47]
	v_mov_b32_e32 v47, 0
	v_mov_b32_e32 v46, 0
	v_add_f32_dpp v4, v4, v4 row_ror:1 row_mask:0xf bank_mask:0xf bound_ctrl:1
	v_mov_b32_dpp v47, v45 row_ror:4 row_mask:0xf bank_mask:0xf
	v_mov_b32_dpp v46, v44 row_ror:4 row_mask:0xf bank_mask:0xf
	v_pk_add_f32 v[44:45], v[44:45], v[46:47]
	v_mov_b32_e32 v47, 0
	v_mov_b32_e32 v46, 0
	v_mov_b32_e32 v50, v4
	s_nop 1
	v_permlane16_swap_b32_e32 v50, v50
	v_mov_b32_dpp v47, v45 row_ror:2 row_mask:0xf bank_mask:0xf
	v_mov_b32_dpp v46, v44 row_ror:2 row_mask:0xf bank_mask:0xf
	v_pk_add_f32 v[44:45], v[44:45], v[46:47]
	v_mov_b32_e32 v47, 0
	v_mov_b32_e32 v46, 0
	s_waitcnt lgkmcnt(0)
	v_add_f32_e32 v4, v4, v50
	v_mov_b32_dpp v47, v45 row_ror:1 row_mask:0xf bank_mask:0xf
	v_mov_b32_dpp v46, v44 row_ror:1 row_mask:0xf bank_mask:0xf
	v_pk_add_f32 v[44:45], v[44:45], v[46:47]
	v_mov_b32_e32 v47, v45
	s_nop 1
	v_permlane16_swap_b32_e32 v47, v47
	v_mov_b32_e32 v46, v44
	s_nop 1
	v_permlane16_swap_b32_e32 v46, v46
	v_mov_b32_e32 v50, v4
	s_nop 1
	v_permlane32_swap_b32_e32 v50, v50
	v_sub_f32_e32 v48, v92, v97
	v_fma_mix_f32 v14, v77, v48, v14 op_sel_hi:[0,0,1]
	s_waitcnt lgkmcnt(1)
	v_pk_add_f32 v[44:45], v[44:45], v[46:47]
	v_mov_b32_e32 v47, v45
	s_nop 1
	v_permlane32_swap_b32_e32 v47, v47
	v_mov_b32_e32 v46, v44
	s_nop 1
	v_permlane32_swap_b32_e32 v46, v46
	s_waitcnt lgkmcnt(2)
	v_add_f32_e32 v4, v4, v50
	s_waitcnt lgkmcnt(0)
	v_pk_add_f32 v[44:45], v[44:45], v[46:47]
	s_nop 0
	v_pk_fma_f32 v[0:1], v[44:45], s[6:7], v[0:1] op_sel_hi:[1,0,0]
	s_nop 0
	v_mul_f32_e32 v44, 0x4b800000, v1
	v_cmp_gt_f32_e32 vcc, s19, v1
	s_nop 1
	v_cndmask_b32_e32 v1, v1, v44, vcc
	v_rsq_f32_e32 v1, v1
	v_mul_f32_e32 v44, v51, v90
	v_mul_f32_e32 v45, 0x45800000, v1
	v_cndmask_b32_e32 v1, v1, v45, vcc
	v_mul_f32_e32 v1, v1, v11
	v_mul_f32_e32 v1, v13, v1
	v_fma_mixlo_f16 v1, v44, v1, 0
	global_store_short v[6:7], v1, off
	v_mul_f32_e32 v1, 0x4b800000, v0
	v_cmp_gt_f32_e32 vcc, s19, v0
	v_mov_b32_e32 v44, 0
	v_mov_b32_e32 v45, 0
	v_cndmask_b32_e32 v0, v0, v1, vcc
	v_rsq_f32_e32 v11, v0
	v_pk_mul_f32 v[0:1], v[8:9], v[8:9]
	v_mul_f32_e32 v46, 0x45800000, v11
	s_nop 0
	v_mov_b32_dpp v44, v0 row_ror:8 row_mask:0xf bank_mask:0xf
	v_mov_b32_dpp v45, v1 row_ror:8 row_mask:0xf bank_mask:0xf
	v_pk_fma_f32 v[0:1], v[8:9], v[8:9], v[44:45]
	v_mov_b32_e32 v44, 0
	v_mov_b32_e32 v45, 0
	v_cndmask_b32_e32 v11, v11, v46, vcc
	v_mov_b32_dpp v44, v0 row_ror:4 row_mask:0xf bank_mask:0xf
	v_mov_b32_dpp v45, v1 row_ror:4 row_mask:0xf bank_mask:0xf
	v_pk_add_f32 v[0:1], v[0:1], v[44:45]
	v_mov_b32_e32 v44, 0
	v_mov_b32_e32 v45, 0
	v_mul_f32_e32 v46, 0xbfb8aa3b, v87
	v_mov_b32_dpp v44, v0 row_ror:2 row_mask:0xf bank_mask:0xf
	v_mov_b32_dpp v45, v1 row_ror:2 row_mask:0xf bank_mask:0xf
	v_pk_add_f32 v[0:1], v[0:1], v[44:45]
	v_mov_b32_e32 v44, 0
	v_mov_b32_e32 v45, 0
	v_exp_f32_e32 v46, v46
	v_mov_b32_dpp v44, v0 row_ror:1 row_mask:0xf bank_mask:0xf
	v_mov_b32_dpp v45, v1 row_ror:1 row_mask:0xf bank_mask:0xf
	v_pk_add_f32 v[0:1], v[0:1], v[44:45]
	v_mov_b32_e32 v44, v0
	s_nop 1
	v_permlane16_swap_b32_e32 v44, v44
	v_mov_b32_e32 v45, v1
	s_nop 1
	v_permlane16_swap_b32_e32 v45, v45
	v_mul_f32_e32 v10, v11, v10
	v_add_f32_e32 v11, 1.0, v46
	v_rcp_f32_e32 v11, v11
	v_mul_f32_e32 v10, v70, v10
	s_waitcnt lgkmcnt(0)
	v_pk_add_f32 v[0:1], v[0:1], v[44:45]
	v_mov_b32_e32 v44, v0
	s_nop 1
	v_permlane32_swap_b32_e32 v44, v44
	v_mov_b32_e32 v45, v1
	s_nop 1
	v_permlane32_swap_b32_e32 v45, v45
	s_waitcnt lgkmcnt(0)
	v_pk_add_f32 v[0:1], v[0:1], v[44:45]
	s_nop 0
	v_pk_fma_f32 v[0:1], v[0:1], s[6:7], v[2:3] op_sel_hi:[1,0,1]
	v_mul_f32_e32 v3, 0xbfb8aa3b, v5
	v_mul_f32_e32 v2, 0x4b800000, v1
	v_cmp_gt_f32_e32 vcc, s19, v1
	v_exp_f32_e32 v3, v3
	s_nop 0
	v_cndmask_b32_e32 v1, v1, v2, vcc
	v_rsq_f32_e32 v1, v1
	v_mul_f32_e32 v2, v11, v87
	v_fma_mixlo_f16 v2, v2, v10, 0
	global_store_short v[6:7], v2, off offset:512
	v_mul_f32_e32 v2, 0x45800000, v1
	v_cndmask_b32_e32 v1, v1, v2, vcc
	v_mul_f32_e32 v1, v9, v1
	v_fma_f32 v1, v71, v1, v72
	v_mul_f32_e32 v2, 0x4b800000, v0
	v_cmp_gt_f32_e32 vcc, s19, v0
	v_fmac_f32_e32 v1, v14, v4
	v_fma_mixlo_f16 v1, v49, v1, 0
	v_cndmask_b32_e32 v0, v0, v2, vcc
	v_rsq_f32_e32 v0, v0
	global_store_short v[6:7], v1, off offset:1024
	v_add_f32_e32 v1, 1.0, v3
	v_rcp_f32_e32 v1, v1
	v_mul_f32_e32 v2, 0x45800000, v0
	v_cndmask_b32_e32 v0, v0, v2, vcc
	v_mul_f32_e32 v0, v0, v8
	v_mul_f32_e32 v1, v1, v5
	v_fma_mixlo_f16 v0, v1, v0, 0
	s_and_b64 vcc, exec, s[0:1]
	global_store_short v[6:7], v0, off offset:1536
	s_cbranch_vccnz .LBB0_1512
